# P6 hand epilogue + nt stores + relaxed first waits; P1 nt stores + relaxed first waits (stores overlap next K-loop start)
# speedup vs baseline: 1.0498x; 1.0386x over previous
.LBB0_169:
	s_mov_b64 s[20:21], 0x80
	s_and_b32 s1, s1, 3
	s_add_i32 m0, s72, 0x18000
	v_lshl_add_u64 v[8:9], v[8:9], 0, s[20:21]
	s_lshl_b32 s76, s0, 6
	s_lshl_b32 s5, s0, 13
	s_lshl_b32 s7, s1, 12
	s_waitcnt vmcnt(2)
	s_barrier
	global_load_lds_dwordx4 v[8:9], off
	v_lshl_add_u64 v[6:7], v[6:7], 0, s[20:21]
	s_add_i32 m0, s72, 0x1a000
	s_add_i32 s77, s72, 0x8000
	s_add_i32 s78, s72, 0xa000
	global_load_lds_dwordx4 v[6:7], off
	v_lshl_add_u64 v[2:3], v[2:3], 0, s[20:21]
	s_mov_b32 m0, s77
	s_add_u32 s30, s64, 0x40080
	global_load_lds_dwordx4 v[2:3], off
	v_lshl_add_u64 v[2:3], v[4:5], 0, s[20:21]
	s_mov_b32 m0, s78
	s_addc_u32 s31, s65, 0
	global_load_lds_dwordx4 v[2:3], off
	s_add_i32 m0, s72, 0x1c000
	v_lshl_add_u64 v[2:3], s[30:31], 0, v[132:133]
	global_load_lds_dwordx4 v[2:3], off
	v_lshl_add_u64 v[2:3], s[30:31], 0, v[136:137]
	s_add_i32 m0, s72, 0x1e000
	v_bfe_u32 v157, v10, 4, 2
	global_load_lds_dwordx4 v[2:3], off
	v_and_b32_e32 v156, 15, v10
	v_lshlrev_b32_e32 v2, 4, v157
	v_lshlrev_b32_e32 v3, 2, v10
	v_lshl_or_b32 v2, v156, 6, v2
	v_and_b32_e32 v3, 32, v3
	v_bitop3_b32 v4, v2, s5, v3 bitop3:0xde
	v_bitop3_b32 v158, v2, s7, v3 bitop3:0xde
	v_lshlrev_b32_e32 v2, 14, v11
	v_and_b32_e32 v2, 0xffff8000, v2
	v_lshl_add_u32 v2, v12, 11, v2
	v_and_b32_e32 v3, 1, v11
	s_cmpk_lt_u32 s6, 0x100
	v_lshl_or_b32 v2, v3, 6, v2
	s_cselect_b64 s[44:45], -1, 0
	s_lshl_b32 s79, s1, 6
	s_ashr_i32 s1, s0, 31
	v_lshl_add_u32 v140, v13, 1, v2
	v_lshlrev_b32_e32 v2, 14, v14
	s_lshl_b64 s[0:1], s[0:1], 11
	v_and_b32_e32 v2, 0xffff8000, v2
	s_waitcnt vmcnt(6)
	s_add_u32 s80, s70, s0
	v_lshl_add_u32 v2, v15, 11, v2
	v_and_b32_e32 v3, 1, v14
	s_addc_u32 s81, s71, s1
	v_lshl_or_b32 v2, v3, 6, v2
	s_add_i32 s85, 0, 0x10000
	s_add_i32 s86, 0, 0x14000
	s_ashr_i32 s82, s3, 31
	s_ashr_i32 s83, s2, 31
	v_mov_b32_e32 v141, v139
	v_lshl_add_u32 v142, v16, 1, v2
	v_mov_b32_e32 v143, v139
	v_mov_b64_e32 v[144:145], 0x1200
	v_mov_b64_e32 v[146:147], 0x11ff
	s_movk_i32 s84, 0x241
	v_add_u32_e32 v159, s85, v158
	v_add_u32_e32 v160, s86, v158
	v_add_u32_e32 v161, 0, v4
	s_mov_b32 s46, 0x3e38aa3b
	v_mbcnt_hi_u32_b32 v162, -1, v1
	s_mov_b32 s98, 0
	s_mov_b32 s87, 0
	s_barrier
	s_branch .LBB0_172

.LBB0_175:
	ds_read_b128 v[148:151], v159
	ds_read_b128 v[152:155], v159 offset:1024
	ds_read_b128 v[164:167], v159 offset:2048
	ds_read_b128 v[168:171], v159 offset:3072
	ds_read_b128 v[172:175], v160
	ds_read_b128 v[176:179], v160 offset:1024
	ds_read_b128 v[180:183], v160 offset:2048
	ds_read_b128 v[184:187], v160 offset:3072
	s_add_u32 s6, s60, 0xfffc0080
	s_addc_u32 s7, s61, -1
	s_cmp_eq_u32 s63, 12
	s_cselect_b32 s67, s5, s7
	s_cselect_b32 s66, s8, s6
	s_cselect_b32 s65, s30, s55
	s_cselect_b32 s64, s31, s49
	v_lshl_add_u64 v[220:221], s[60:61], 0, v[140:141]
	s_add_i32 m0, s72, 0xc000
	ds_read_b128 v[188:191], v161
	ds_read_b128 v[192:195], v161 offset:1024
	ds_read_b128 v[196:199], v161 offset:2048
	ds_read_b128 v[200:203], v161 offset:3072
	ds_read_b128 v[204:207], v161 offset:4096
	ds_read_b128 v[208:211], v161 offset:5120
	ds_read_b128 v[212:215], v161 offset:6144
	ds_read_b128 v[216:219], v161 offset:7168
	global_load_lds_dwordx4 v[220:221], off
	v_lshl_add_u64 v[220:221], s[60:61], 0, v[142:143]
	s_add_i32 m0, s72, 0xe000
	s_nop 0
	global_load_lds_dwordx4 v[220:221], off
	s_cmp_lg_u32 s98, 0
	s_cbranch_scc1 .Lrwg1a_relaxed
	s_waitcnt vmcnt(8)
.Lrwg1a_done:
	s_waitcnt lgkmcnt(0)
	s_barrier
	s_setprio 1
	s_waitcnt lgkmcnt(0)
	v_mfma_f32_16x16x32_bf16 v[126:129], v[148:151], v[188:191], v[126:129]
	v_mfma_f32_16x16x32_bf16 v[122:125], v[164:167], v[188:191], v[122:125]
	v_mfma_f32_16x16x32_bf16 v[110:113], v[148:151], v[196:199], v[110:113]
	v_mfma_f32_16x16x32_bf16 v[106:109], v[164:167], v[196:199], v[106:109]
	v_mfma_f32_16x16x32_bf16 v[94:97], v[148:151], v[204:207], v[94:97]
	v_mfma_f32_16x16x32_bf16 v[90:93], v[164:167], v[204:207], v[90:93]
	v_mfma_f32_16x16x32_bf16 v[78:81], v[148:151], v[212:215], v[78:81]
	v_mfma_f32_16x16x32_bf16 v[74:77], v[164:167], v[212:215], v[74:77]
	v_mfma_f32_16x16x32_bf16 v[126:129], v[152:155], v[192:195], v[126:129]
	v_mfma_f32_16x16x32_bf16 v[122:125], v[168:171], v[192:195], v[122:125]
	v_mfma_f32_16x16x32_bf16 v[110:113], v[152:155], v[200:203], v[110:113]
	v_mfma_f32_16x16x32_bf16 v[106:109], v[168:171], v[200:203], v[106:109]
	v_mfma_f32_16x16x32_bf16 v[94:97], v[152:155], v[208:211], v[94:97]
	v_mfma_f32_16x16x32_bf16 v[90:93], v[168:171], v[208:211], v[90:93]
	v_mfma_f32_16x16x32_bf16 v[78:81], v[152:155], v[216:219], v[78:81]
	v_mfma_f32_16x16x32_bf16 v[74:77], v[168:171], v[216:219], v[74:77]
	s_setprio 0
	s_setprio 1
	v_mfma_f32_16x16x32_bf16 v[118:121], v[172:175], v[188:191], v[118:121]
	v_mfma_f32_16x16x32_bf16 v[114:117], v[180:183], v[188:191], v[114:117]
	v_mfma_f32_16x16x32_bf16 v[102:105], v[172:175], v[196:199], v[102:105]
	v_mfma_f32_16x16x32_bf16 v[98:101], v[180:183], v[196:199], v[98:101]
	v_mfma_f32_16x16x32_bf16 v[86:89], v[172:175], v[204:207], v[86:89]
	v_mfma_f32_16x16x32_bf16 v[82:85], v[180:183], v[204:207], v[82:85]
	v_mfma_f32_16x16x32_bf16 v[70:73], v[172:175], v[212:215], v[70:73]
	v_mfma_f32_16x16x32_bf16 v[66:69], v[180:183], v[212:215], v[66:69]
	v_mfma_f32_16x16x32_bf16 v[118:121], v[176:179], v[192:195], v[118:121]
	v_mfma_f32_16x16x32_bf16 v[114:117], v[184:187], v[192:195], v[114:117]
	v_mfma_f32_16x16x32_bf16 v[102:105], v[176:179], v[200:203], v[102:105]
	v_mfma_f32_16x16x32_bf16 v[98:101], v[184:187], v[200:203], v[98:101]
	v_mfma_f32_16x16x32_bf16 v[86:89], v[176:179], v[208:211], v[86:89]
	v_mfma_f32_16x16x32_bf16 v[82:85], v[184:187], v[208:211], v[82:85]
	v_mfma_f32_16x16x32_bf16 v[70:73], v[176:179], v[216:219], v[70:73]
	v_mfma_f32_16x16x32_bf16 v[66:69], v[184:187], v[216:219], v[66:69]
	s_setprio 0
	s_barrier
	s_add_i32 s6, s85, s47
	v_lshl_add_u64 v[220:221], s[64:65], 0, v[132:133]
	s_mov_b32 m0, s6
	ds_read_b128 v[188:191], v161 offset:16384
	ds_read_b128 v[192:195], v161 offset:17408
	ds_read_b128 v[196:199], v161 offset:18432
	ds_read_b128 v[200:203], v161 offset:19456
	ds_read_b128 v[204:207], v161 offset:20480
	ds_read_b128 v[208:211], v161 offset:21504
	ds_read_b128 v[212:215], v161 offset:22528
	ds_read_b128 v[216:219], v161 offset:23552
	global_load_lds_dwordx4 v[220:221], off
	s_add_i32 m0, s6, 0x2000
	s_add_u32 s6, s64, 0x40000
	v_lshl_add_u64 v[222:223], s[64:65], 0, v[136:137]
	s_addc_u32 s7, s65, 0
	s_add_i32 s88, s86, s47
	global_load_lds_dwordx4 v[222:223], off
	v_lshl_add_u64 v[224:225], s[6:7], 0, v[132:133]
	s_mov_b32 m0, s88
	v_lshl_add_u64 v[226:227], s[66:67], 0, v[134:135]
	global_load_lds_dwordx4 v[224:225], off
	v_lshl_add_u64 v[224:225], s[6:7], 0, v[136:137]
	s_add_i32 m0, s88, 0x2000
	s_nop 0
	global_load_lds_dwordx4 v[224:225], off
	v_lshl_add_u64 v[224:225], s[66:67], 0, v[130:131]
	s_mov_b32 m0, s72
	s_nop 0
	global_load_lds_dwordx4 v[224:225], off
	s_mov_b32 m0, s73
	s_nop 0
	global_load_lds_dwordx4 v[226:227], off
	s_cmp_lg_u32 s98, 0
	s_cbranch_scc1 .Lrwg1b_relaxed
	s_waitcnt vmcnt(8)
.Lrwg1b_done:
	s_waitcnt lgkmcnt(0)
	s_barrier
	s_setprio 1
	s_waitcnt lgkmcnt(0)
	v_mfma_f32_16x16x32_bf16 v[62:65], v[148:151], v[188:191], v[62:65]
	v_mfma_f32_16x16x32_bf16 v[58:61], v[164:167], v[188:191], v[58:61]
	v_mfma_f32_16x16x32_bf16 v[46:49], v[148:151], v[196:199], v[46:49]
	v_mfma_f32_16x16x32_bf16 v[42:45], v[164:167], v[196:199], v[42:45]
	v_mfma_f32_16x16x32_bf16 v[30:33], v[148:151], v[204:207], v[30:33]
	v_mfma_f32_16x16x32_bf16 v[26:29], v[164:167], v[204:207], v[26:29]
	v_mfma_f32_16x16x32_bf16 v[14:17], v[148:151], v[212:215], v[14:17]
	v_mfma_f32_16x16x32_bf16 v[10:13], v[164:167], v[212:215], v[10:13]
	v_mfma_f32_16x16x32_bf16 v[62:65], v[152:155], v[192:195], v[62:65]
	v_mfma_f32_16x16x32_bf16 v[58:61], v[168:171], v[192:195], v[58:61]
	v_mfma_f32_16x16x32_bf16 v[46:49], v[152:155], v[200:203], v[46:49]
	v_mfma_f32_16x16x32_bf16 v[42:45], v[168:171], v[200:203], v[42:45]
	v_mfma_f32_16x16x32_bf16 v[30:33], v[152:155], v[208:211], v[30:33]
	v_mfma_f32_16x16x32_bf16 v[26:29], v[168:171], v[208:211], v[26:29]
	v_mfma_f32_16x16x32_bf16 v[14:17], v[152:155], v[216:219], v[14:17]
	v_mfma_f32_16x16x32_bf16 v[10:13], v[168:171], v[216:219], v[10:13]
	s_setprio 0
	s_setprio 1
	v_mfma_f32_16x16x32_bf16 v[54:57], v[172:175], v[188:191], v[54:57]
	v_mfma_f32_16x16x32_bf16 v[50:53], v[180:183], v[188:191], v[50:53]
	v_mfma_f32_16x16x32_bf16 v[38:41], v[172:175], v[196:199], v[38:41]
	v_mfma_f32_16x16x32_bf16 v[34:37], v[180:183], v[196:199], v[34:37]
	v_mfma_f32_16x16x32_bf16 v[22:25], v[172:175], v[204:207], v[22:25]
	v_mfma_f32_16x16x32_bf16 v[18:21], v[180:183], v[204:207], v[18:21]
	v_mfma_f32_16x16x32_bf16 v[6:9], v[172:175], v[212:215], v[6:9]
	v_mfma_f32_16x16x32_bf16 v[2:5], v[180:183], v[212:215], v[2:5]
	v_mfma_f32_16x16x32_bf16 v[54:57], v[176:179], v[192:195], v[54:57]
	v_mfma_f32_16x16x32_bf16 v[50:53], v[184:187], v[192:195], v[50:53]
	v_mfma_f32_16x16x32_bf16 v[38:41], v[176:179], v[200:203], v[38:41]
	v_mfma_f32_16x16x32_bf16 v[34:37], v[184:187], v[200:203], v[34:37]
	v_mfma_f32_16x16x32_bf16 v[22:25], v[176:179], v[208:211], v[22:25]
	v_mfma_f32_16x16x32_bf16 v[18:21], v[184:187], v[208:211], v[18:21]
	v_mfma_f32_16x16x32_bf16 v[6:9], v[176:179], v[216:219], v[6:9]
	v_mfma_f32_16x16x32_bf16 v[2:5], v[184:187], v[216:219], v[2:5]
	s_setprio 0
	s_barrier
	s_add_i32 s88, 0, 0x18000
	v_add_u32_e32 v138, s88, v158
	s_add_i32 s89, 0, 0x1c000
	ds_read_b128 v[148:151], v138
	ds_read_b128 v[152:155], v138 offset:1024
	ds_read_b128 v[164:167], v138 offset:2048
	ds_read_b128 v[168:171], v138 offset:3072
	v_add_u32_e32 v138, s89, v158
	ds_read_b128 v[172:175], v138
	ds_read_b128 v[176:179], v138 offset:1024
	ds_read_b128 v[180:183], v138 offset:2048
	ds_read_b128 v[184:187], v138 offset:3072
	s_add_u32 s6, s66, 0x40000
	s_addc_u32 s7, s67, 0
	s_mov_b32 m0, s74
	v_lshl_add_u64 v[228:229], s[6:7], 0, v[130:131]
	ds_read_b128 v[188:191], v161 offset:32768
	ds_read_b128 v[192:195], v161 offset:33792
	ds_read_b128 v[196:199], v161 offset:34816
	ds_read_b128 v[200:203], v161 offset:35840
	ds_read_b128 v[204:207], v161 offset:36864
	ds_read_b128 v[208:211], v161 offset:37888
	ds_read_b128 v[212:215], v161 offset:38912
	ds_read_b128 v[216:219], v161 offset:39936
	global_load_lds_dwordx4 v[228:229], off
	v_lshl_add_u64 v[228:229], s[6:7], 0, v[134:135]
	s_mov_b32 m0, s75
	s_nop 0
	global_load_lds_dwordx4 v[228:229], off
	s_waitcnt vmcnt(8)
	s_waitcnt lgkmcnt(0)
	s_barrier
	s_setprio 1
	s_waitcnt lgkmcnt(0)
	v_mfma_f32_16x16x32_bf16 v[126:129], v[148:151], v[188:191], v[126:129]
	v_mfma_f32_16x16x32_bf16 v[122:125], v[164:167], v[188:191], v[122:125]
	v_mfma_f32_16x16x32_bf16 v[110:113], v[148:151], v[196:199], v[110:113]
	v_mfma_f32_16x16x32_bf16 v[106:109], v[164:167], v[196:199], v[106:109]
	v_mfma_f32_16x16x32_bf16 v[94:97], v[148:151], v[204:207], v[94:97]
	v_mfma_f32_16x16x32_bf16 v[90:93], v[164:167], v[204:207], v[90:93]
	v_mfma_f32_16x16x32_bf16 v[78:81], v[148:151], v[212:215], v[78:81]
	v_mfma_f32_16x16x32_bf16 v[74:77], v[164:167], v[212:215], v[74:77]
	v_mfma_f32_16x16x32_bf16 v[126:129], v[152:155], v[192:195], v[126:129]
	v_mfma_f32_16x16x32_bf16 v[122:125], v[168:171], v[192:195], v[122:125]
	v_mfma_f32_16x16x32_bf16 v[110:113], v[152:155], v[200:203], v[110:113]
	v_mfma_f32_16x16x32_bf16 v[106:109], v[168:171], v[200:203], v[106:109]
	v_mfma_f32_16x16x32_bf16 v[94:97], v[152:155], v[208:211], v[94:97]
	v_mfma_f32_16x16x32_bf16 v[90:93], v[168:171], v[208:211], v[90:93]
	v_mfma_f32_16x16x32_bf16 v[78:81], v[152:155], v[216:219], v[78:81]
	v_mfma_f32_16x16x32_bf16 v[74:77], v[168:171], v[216:219], v[74:77]
	s_setprio 0
	s_setprio 1
	v_mfma_f32_16x16x32_bf16 v[118:121], v[172:175], v[188:191], v[118:121]
	v_mfma_f32_16x16x32_bf16 v[114:117], v[180:183], v[188:191], v[114:117]
	v_mfma_f32_16x16x32_bf16 v[102:105], v[172:175], v[196:199], v[102:105]
	v_mfma_f32_16x16x32_bf16 v[98:101], v[180:183], v[196:199], v[98:101]
	v_mfma_f32_16x16x32_bf16 v[86:89], v[172:175], v[204:207], v[86:89]
	v_mfma_f32_16x16x32_bf16 v[82:85], v[180:183], v[204:207], v[82:85]
	v_mfma_f32_16x16x32_bf16 v[70:73], v[172:175], v[212:215], v[70:73]
	v_mfma_f32_16x16x32_bf16 v[66:69], v[180:183], v[212:215], v[66:69]
	v_mfma_f32_16x16x32_bf16 v[118:121], v[176:179], v[192:195], v[118:121]
	v_mfma_f32_16x16x32_bf16 v[114:117], v[184:187], v[192:195], v[114:117]
	v_mfma_f32_16x16x32_bf16 v[102:105], v[176:179], v[200:203], v[102:105]
	v_mfma_f32_16x16x32_bf16 v[98:101], v[184:187], v[200:203], v[98:101]
	v_mfma_f32_16x16x32_bf16 v[86:89], v[176:179], v[208:211], v[86:89]
	v_mfma_f32_16x16x32_bf16 v[82:85], v[184:187], v[208:211], v[82:85]
	v_mfma_f32_16x16x32_bf16 v[70:73], v[176:179], v[216:219], v[70:73]
	v_mfma_f32_16x16x32_bf16 v[66:69], v[184:187], v[216:219], v[66:69]
	s_setprio 0
	s_barrier
	s_add_i32 s6, s88, s47
	v_lshl_add_u64 v[220:221], v[220:221], 0, s[20:21]
	s_mov_b32 m0, s6
	ds_read_b128 v[188:191], v161 offset:49152
	ds_read_b128 v[192:195], v161 offset:50176
	ds_read_b128 v[196:199], v161 offset:51200
	ds_read_b128 v[200:203], v161 offset:52224
	ds_read_b128 v[204:207], v161 offset:53248
	ds_read_b128 v[208:211], v161 offset:54272
	ds_read_b128 v[212:215], v161 offset:55296
	ds_read_b128 v[216:219], v161 offset:56320
	global_load_lds_dwordx4 v[220:221], off
	s_add_i32 m0, s6, 0x2000
	s_add_u32 s6, s64, 0x40080
	v_lshl_add_u64 v[220:221], v[222:223], 0, s[20:21]
	s_addc_u32 s7, s65, 0
	s_add_i32 s64, s89, s47
	global_load_lds_dwordx4 v[220:221], off
	v_lshl_add_u64 v[220:221], s[6:7], 0, v[132:133]
	s_mov_b32 m0, s64
	s_nop 0
	global_load_lds_dwordx4 v[220:221], off
	v_lshl_add_u64 v[220:221], s[6:7], 0, v[136:137]
	s_add_i32 m0, s64, 0x2000
	s_nop 0
	global_load_lds_dwordx4 v[220:221], off
	v_lshl_add_u64 v[220:221], v[224:225], 0, s[20:21]
	s_mov_b32 m0, s77
	s_nop 0
	global_load_lds_dwordx4 v[220:221], off
	v_lshl_add_u64 v[220:221], v[226:227], 0, s[20:21]
	s_mov_b32 m0, s78
	s_nop 0
	global_load_lds_dwordx4 v[220:221], off
	s_waitcnt vmcnt(8)
	s_waitcnt lgkmcnt(0)
	s_barrier
	s_setprio 1
	s_waitcnt lgkmcnt(0)
	v_mfma_f32_16x16x32_bf16 v[62:65], v[148:151], v[188:191], v[62:65]
	v_mfma_f32_16x16x32_bf16 v[58:61], v[164:167], v[188:191], v[58:61]
	v_mfma_f32_16x16x32_bf16 v[46:49], v[148:151], v[196:199], v[46:49]
	v_mfma_f32_16x16x32_bf16 v[42:45], v[164:167], v[196:199], v[42:45]
	v_mfma_f32_16x16x32_bf16 v[30:33], v[148:151], v[204:207], v[30:33]
	v_mfma_f32_16x16x32_bf16 v[26:29], v[164:167], v[204:207], v[26:29]
	v_mfma_f32_16x16x32_bf16 v[14:17], v[148:151], v[212:215], v[14:17]
	v_mfma_f32_16x16x32_bf16 v[10:13], v[164:167], v[212:215], v[10:13]
	v_mfma_f32_16x16x32_bf16 v[62:65], v[152:155], v[192:195], v[62:65]
	v_mfma_f32_16x16x32_bf16 v[58:61], v[168:171], v[192:195], v[58:61]
	v_mfma_f32_16x16x32_bf16 v[46:49], v[152:155], v[200:203], v[46:49]
	v_mfma_f32_16x16x32_bf16 v[42:45], v[168:171], v[200:203], v[42:45]
	v_mfma_f32_16x16x32_bf16 v[30:33], v[152:155], v[208:211], v[30:33]
	v_mfma_f32_16x16x32_bf16 v[26:29], v[168:171], v[208:211], v[26:29]
	v_mfma_f32_16x16x32_bf16 v[14:17], v[152:155], v[216:219], v[14:17]
	v_mfma_f32_16x16x32_bf16 v[10:13], v[168:171], v[216:219], v[10:13]
	s_setprio 0
	s_setprio 1
	v_mfma_f32_16x16x32_bf16 v[54:57], v[172:175], v[188:191], v[54:57]
	v_mfma_f32_16x16x32_bf16 v[50:53], v[180:183], v[188:191], v[50:53]
	v_mfma_f32_16x16x32_bf16 v[38:41], v[172:175], v[196:199], v[38:41]
	v_mfma_f32_16x16x32_bf16 v[34:37], v[180:183], v[196:199], v[34:37]
	v_mfma_f32_16x16x32_bf16 v[22:25], v[172:175], v[204:207], v[22:25]
	v_mfma_f32_16x16x32_bf16 v[18:21], v[180:183], v[204:207], v[18:21]
	v_mfma_f32_16x16x32_bf16 v[6:9], v[172:175], v[212:215], v[6:9]
	v_mfma_f32_16x16x32_bf16 v[2:5], v[180:183], v[212:215], v[2:5]
	v_mfma_f32_16x16x32_bf16 v[54:57], v[176:179], v[192:195], v[54:57]
	v_mfma_f32_16x16x32_bf16 v[50:53], v[184:187], v[192:195], v[50:53]
	v_mfma_f32_16x16x32_bf16 v[38:41], v[176:179], v[200:203], v[38:41]
	v_mfma_f32_16x16x32_bf16 v[34:37], v[184:187], v[200:203], v[34:37]
	v_mfma_f32_16x16x32_bf16 v[22:25], v[176:179], v[208:211], v[22:25]
	v_mfma_f32_16x16x32_bf16 v[18:21], v[184:187], v[208:211], v[18:21]
	v_mfma_f32_16x16x32_bf16 v[6:9], v[176:179], v[216:219], v[6:9]
	v_mfma_f32_16x16x32_bf16 v[2:5], v[184:187], v[216:219], v[2:5]
	s_setprio 0
	s_barrier
	s_add_i32 s63, s63, 2
	s_add_u32 s60, s60, 0x100
	s_addc_u32 s61, s61, 0
	s_add_u32 s49, s49, 0x100
	s_addc_u32 s55, s55, 0
	s_cmp_gt_u32 s63, 13
	s_cbranch_scc0 .LBB0_175
	s_and_b64 vcc, exec, s[44:45]
	s_cbranch_vccz .LBB0_178
	s_barrier

.LBB0_192:
	v_and_b32_e32 v149, 64, v162
	v_xor_b32_e32 v148, 1, v162
	v_add_u32_e32 v149, 64, v149
	v_cmp_lt_i32_e32 vcc, v148, v149
	v_xor_b32_e32 v151, 2, v162
	s_ashr_i32 s5, s4, 31
	v_cndmask_b32_e32 v148, v162, v148, vcc
	v_lshlrev_b32_e32 v150, 2, v148
	v_add_f32_e32 v148, 0, v126
	v_add_f32_e32 v148, v148, v110
	v_add_f32_e32 v148, v148, v94
	v_add_f32_e32 v148, v148, v78
	v_add_f32_e32 v148, v148, v62
	v_add_f32_e32 v148, v148, v46
	v_add_f32_e32 v148, v148, v30
	v_add_f32_e32 v148, v148, v14
	ds_bpermute_b32 v152, v150, v148
	v_cmp_lt_i32_e32 vcc, v151, v149
	s_lshl_b64 s[6:7], s[4:5], 12
	s_add_u32 s5, s80, s6
	v_cndmask_b32_e32 v151, v162, v151, vcc
	v_lshlrev_b32_e32 v151, 2, v151
	s_waitcnt lgkmcnt(0)
	v_add_f32_e32 v148, v148, v152
	ds_bpermute_b32 v153, v151, v148
	v_xor_b32_e32 v152, 4, v162
	v_cmp_lt_i32_e32 vcc, v152, v149
	s_addc_u32 s30, s81, s7
	s_lshl_b64 s[6:7], s[8:9], 2
	v_cndmask_b32_e32 v152, v162, v152, vcc
	v_lshlrev_b32_e32 v152, 2, v152
	s_waitcnt lgkmcnt(0)
	v_add_f32_e32 v148, v148, v153
	ds_bpermute_b32 v154, v152, v148
	v_xor_b32_e32 v153, 8, v162
	v_cmp_lt_i32_e32 vcc, v153, v149
	s_add_u32 s6, s5, s6
	s_addc_u32 s7, s30, s7
	v_cndmask_b32_e32 v149, v162, v153, vcc
	v_lshlrev_b32_e32 v153, 2, v149
	s_waitcnt lgkmcnt(0)
	v_add_f32_e32 v154, v148, v154
	ds_bpermute_b32 v155, v153, v154
	v_lshlrev_b32_e32 v148, 3, v163
	v_ashrrev_i32_e32 v149, 31, v148
	v_lshl_add_u64 v[148:149], v[148:149], 2, s[6:7]
	v_cmp_eq_u32_e32 vcc, 0, v138
	s_and_saveexec_b64 s[62:63], vcc
	s_cbranch_execz .LBB0_194
	s_waitcnt lgkmcnt(0)
	v_add_f32_e32 v154, v154, v155
	global_store_dword v[148:149], v154, off nt
	s_bitset1_b32 s98, 0
.LBB0_194:
	s_or_b64 exec, exec, s[62:63]
	v_add_f32_e32 v154, 0, v127
	v_add_f32_e32 v154, v154, v111
	v_add_f32_e32 v154, v154, v95
	v_add_f32_e32 v154, v154, v79
	v_add_f32_e32 v154, v154, v63
	v_add_f32_e32 v154, v154, v47
	v_add_f32_e32 v154, v154, v31
	v_add_f32_e32 v154, v154, v15
	s_waitcnt lgkmcnt(0)
	ds_bpermute_b32 v155, v150, v154
	s_waitcnt lgkmcnt(0)
	v_add_f32_e32 v154, v154, v155
	ds_bpermute_b32 v155, v151, v154
	s_waitcnt lgkmcnt(0)
	v_add_f32_e32 v154, v154, v155
	ds_bpermute_b32 v155, v152, v154
	s_waitcnt lgkmcnt(0)
	v_add_f32_e32 v154, v154, v155
	ds_bpermute_b32 v155, v153, v154
	s_and_saveexec_b64 s[62:63], vcc
	s_cbranch_execz .LBB0_196
	s_waitcnt lgkmcnt(0)
	v_add_f32_e32 v154, v154, v155
	global_store_dword v[148:149], v154, off offset:4 nt
	s_bitset1_b32 s98, 1
.LBB0_196:
	s_or_b64 exec, exec, s[62:63]
	v_add_f32_e32 v154, 0, v128
	v_add_f32_e32 v154, v154, v112
	v_add_f32_e32 v154, v154, v96
	v_add_f32_e32 v154, v154, v80
	v_add_f32_e32 v154, v154, v64
	v_add_f32_e32 v154, v154, v48
	v_add_f32_e32 v154, v154, v32
	v_add_f32_e32 v154, v154, v16
	s_waitcnt lgkmcnt(0)
	ds_bpermute_b32 v155, v150, v154
	s_waitcnt lgkmcnt(0)
	v_add_f32_e32 v154, v154, v155
	ds_bpermute_b32 v155, v151, v154
	s_waitcnt lgkmcnt(0)
	v_add_f32_e32 v154, v154, v155
	ds_bpermute_b32 v155, v152, v154
	s_waitcnt lgkmcnt(0)
	v_add_f32_e32 v154, v154, v155
	ds_bpermute_b32 v155, v153, v154
	s_and_saveexec_b64 s[62:63], vcc
	s_cbranch_execz .LBB0_198
	s_waitcnt lgkmcnt(0)
	v_add_f32_e32 v154, v154, v155
	global_store_dword v[148:149], v154, off offset:8 nt
	s_bitset1_b32 s98, 2
.LBB0_198:
	s_or_b64 exec, exec, s[62:63]
	v_add_f32_e32 v154, 0, v129
	v_add_f32_e32 v154, v154, v113
	v_add_f32_e32 v154, v154, v97
	v_add_f32_e32 v154, v154, v81
	v_add_f32_e32 v154, v154, v65
	v_add_f32_e32 v154, v154, v49
	v_add_f32_e32 v154, v154, v33
	v_add_f32_e32 v154, v154, v17
	s_waitcnt lgkmcnt(0)
	ds_bpermute_b32 v155, v150, v154
	s_waitcnt lgkmcnt(0)
	v_add_f32_e32 v154, v154, v155
	ds_bpermute_b32 v155, v151, v154
	s_waitcnt lgkmcnt(0)
	v_add_f32_e32 v154, v154, v155
	ds_bpermute_b32 v155, v152, v154
	s_waitcnt lgkmcnt(0)
	v_add_f32_e32 v154, v154, v155
	ds_bpermute_b32 v155, v153, v154
	s_and_saveexec_b64 s[62:63], vcc
	s_cbranch_execz .LBB0_200
	s_waitcnt lgkmcnt(0)
	v_add_f32_e32 v154, v154, v155
	global_store_dword v[148:149], v154, off offset:12 nt
	s_bitset1_b32 s98, 3
.LBB0_200:
	s_or_b64 exec, exec, s[62:63]
	v_add_f32_e32 v154, 0, v122
	v_add_f32_e32 v154, v154, v106
	v_add_f32_e32 v154, v154, v90
	v_add_f32_e32 v154, v154, v74
	v_add_f32_e32 v154, v154, v58
	v_add_f32_e32 v154, v154, v42
	v_add_f32_e32 v154, v154, v26
	v_add_f32_e32 v154, v154, v10
	s_waitcnt lgkmcnt(0)
	ds_bpermute_b32 v155, v150, v154
	s_waitcnt lgkmcnt(0)
	v_add_f32_e32 v154, v154, v155
	ds_bpermute_b32 v155, v151, v154
	s_waitcnt lgkmcnt(0)
	v_add_f32_e32 v154, v154, v155
	ds_bpermute_b32 v155, v152, v154
	s_waitcnt lgkmcnt(0)
	v_add_f32_e32 v154, v154, v155
	ds_bpermute_b32 v155, v153, v154
	s_and_saveexec_b64 s[62:63], vcc
	s_cbranch_execz .LBB0_202
	s_waitcnt lgkmcnt(0)
	v_add_f32_e32 v154, v154, v155
	global_store_dword v[148:149], v154, off offset:16 nt
	s_bitset1_b32 s98, 4
.LBB0_202:
	s_or_b64 exec, exec, s[62:63]
	v_add_f32_e32 v154, 0, v123
	v_add_f32_e32 v154, v154, v107
	v_add_f32_e32 v154, v154, v91
	v_add_f32_e32 v154, v154, v75
	v_add_f32_e32 v154, v154, v59
	v_add_f32_e32 v154, v154, v43
	v_add_f32_e32 v154, v154, v27
	v_add_f32_e32 v154, v154, v11
	s_waitcnt lgkmcnt(0)
	ds_bpermute_b32 v155, v150, v154
	s_waitcnt lgkmcnt(0)
	v_add_f32_e32 v154, v154, v155
	ds_bpermute_b32 v155, v151, v154
	s_waitcnt lgkmcnt(0)
	v_add_f32_e32 v154, v154, v155
	ds_bpermute_b32 v155, v152, v154
	s_waitcnt lgkmcnt(0)
	v_add_f32_e32 v154, v154, v155
	ds_bpermute_b32 v155, v153, v154
	s_and_saveexec_b64 s[62:63], vcc
	s_cbranch_execz .LBB0_204
	s_waitcnt lgkmcnt(0)
	v_add_f32_e32 v154, v154, v155
	global_store_dword v[148:149], v154, off offset:20 nt
	s_bitset1_b32 s98, 5
.LBB0_204:
	s_or_b64 exec, exec, s[62:63]
	v_add_f32_e32 v154, 0, v124
	v_add_f32_e32 v154, v154, v108
	v_add_f32_e32 v154, v154, v92
	v_add_f32_e32 v154, v154, v76
	v_add_f32_e32 v154, v154, v60
	v_add_f32_e32 v154, v154, v44
	v_add_f32_e32 v154, v154, v28
	v_add_f32_e32 v154, v154, v12
	s_waitcnt lgkmcnt(0)
	ds_bpermute_b32 v155, v150, v154
	s_waitcnt lgkmcnt(0)
	v_add_f32_e32 v154, v154, v155
	ds_bpermute_b32 v155, v151, v154
	s_waitcnt lgkmcnt(0)
	v_add_f32_e32 v154, v154, v155
	ds_bpermute_b32 v155, v152, v154
	s_waitcnt lgkmcnt(0)
	v_add_f32_e32 v154, v154, v155
	ds_bpermute_b32 v155, v153, v154
	s_and_saveexec_b64 s[62:63], vcc
	s_cbranch_execz .LBB0_206
	s_waitcnt lgkmcnt(0)
	v_add_f32_e32 v154, v154, v155
	global_store_dword v[148:149], v154, off offset:24 nt
	s_bitset1_b32 s98, 6
.LBB0_206:
	s_or_b64 exec, exec, s[62:63]
	v_add_f32_e32 v154, 0, v125
	v_add_f32_e32 v154, v154, v109
	v_add_f32_e32 v154, v154, v93
	v_add_f32_e32 v154, v154, v77
	v_add_f32_e32 v154, v154, v61
	v_add_f32_e32 v154, v154, v45
	v_add_f32_e32 v154, v154, v29
	v_add_f32_e32 v154, v154, v13
	s_waitcnt lgkmcnt(0)
	ds_bpermute_b32 v155, v150, v154
	s_waitcnt lgkmcnt(0)
	v_add_f32_e32 v154, v154, v155
	ds_bpermute_b32 v155, v151, v154
	s_waitcnt lgkmcnt(0)
	v_add_f32_e32 v154, v154, v155
	ds_bpermute_b32 v155, v152, v154
	s_waitcnt lgkmcnt(0)
	v_add_f32_e32 v154, v154, v155
	ds_bpermute_b32 v155, v153, v154
	s_and_saveexec_b64 s[62:63], vcc
	s_cbranch_execz .LBB0_208
	s_waitcnt lgkmcnt(0)
	v_add_f32_e32 v154, v154, v155
	global_store_dword v[148:149], v154, off offset:28 nt
	s_bitset1_b32 s98, 7
.LBB0_208:
	s_or_b64 exec, exec, s[62:63]
	v_add_f32_e32 v154, 0, v118
	v_add_f32_e32 v154, v154, v102
	v_add_f32_e32 v154, v154, v86
	v_add_f32_e32 v154, v154, v70
	v_add_f32_e32 v154, v154, v54
	v_add_f32_e32 v154, v154, v38
	v_add_f32_e32 v154, v154, v22
	v_add_f32_e32 v154, v154, v6
	s_waitcnt lgkmcnt(0)
	ds_bpermute_b32 v155, v150, v154
	s_waitcnt lgkmcnt(0)
	v_add_f32_e32 v154, v154, v155
	ds_bpermute_b32 v155, v151, v154
	s_waitcnt lgkmcnt(0)
	v_add_f32_e32 v154, v154, v155
	ds_bpermute_b32 v155, v152, v154
	s_waitcnt lgkmcnt(0)
	v_add_f32_e32 v154, v154, v155
	ds_bpermute_b32 v155, v153, v154
	s_and_saveexec_b64 s[62:63], vcc
	s_cbranch_execz .LBB0_210
	s_waitcnt lgkmcnt(0)
	v_add_f32_e32 v154, v154, v155
	global_store_dword v[148:149], v154, off offset:128 nt
	s_bitset1_b32 s98, 8
.LBB0_210:
	s_or_b64 exec, exec, s[62:63]
	v_add_f32_e32 v154, 0, v119
	v_add_f32_e32 v154, v154, v103
	v_add_f32_e32 v154, v154, v87
	v_add_f32_e32 v154, v154, v71
	v_add_f32_e32 v154, v154, v55
	v_add_f32_e32 v154, v154, v39
	v_add_f32_e32 v154, v154, v23
	v_add_f32_e32 v154, v154, v7
	s_waitcnt lgkmcnt(0)
	ds_bpermute_b32 v155, v150, v154
	s_waitcnt lgkmcnt(0)
	v_add_f32_e32 v154, v154, v155
	ds_bpermute_b32 v155, v151, v154
	s_waitcnt lgkmcnt(0)
	v_add_f32_e32 v154, v154, v155
	ds_bpermute_b32 v155, v152, v154
	s_waitcnt lgkmcnt(0)
	v_add_f32_e32 v154, v154, v155
	ds_bpermute_b32 v155, v153, v154
	s_and_saveexec_b64 s[62:63], vcc
	s_cbranch_execz .LBB0_212
	s_waitcnt lgkmcnt(0)
	v_add_f32_e32 v154, v154, v155
	global_store_dword v[148:149], v154, off offset:132 nt
	s_bitset1_b32 s98, 9
.LBB0_212:
	s_or_b64 exec, exec, s[62:63]
	v_add_f32_e32 v154, 0, v120
	v_add_f32_e32 v154, v154, v104
	v_add_f32_e32 v154, v154, v88
	v_add_f32_e32 v154, v154, v72
	v_add_f32_e32 v154, v154, v56
	v_add_f32_e32 v154, v154, v40
	v_add_f32_e32 v154, v154, v24
	v_add_f32_e32 v154, v154, v8
	s_waitcnt lgkmcnt(0)
	ds_bpermute_b32 v155, v150, v154
	s_waitcnt lgkmcnt(0)
	v_add_f32_e32 v154, v154, v155
	ds_bpermute_b32 v155, v151, v154
	s_waitcnt lgkmcnt(0)
	v_add_f32_e32 v154, v154, v155
	ds_bpermute_b32 v155, v152, v154
	s_waitcnt lgkmcnt(0)
	v_add_f32_e32 v154, v154, v155
	ds_bpermute_b32 v155, v153, v154
	s_and_saveexec_b64 s[62:63], vcc
	s_cbranch_execz .LBB0_214
	s_waitcnt lgkmcnt(0)
	v_add_f32_e32 v154, v154, v155
	global_store_dword v[148:149], v154, off offset:136 nt
	s_bitset1_b32 s98, 10
.LBB0_214:
	s_or_b64 exec, exec, s[62:63]
	v_add_f32_e32 v154, 0, v121
	v_add_f32_e32 v154, v154, v105
	v_add_f32_e32 v154, v154, v89
	v_add_f32_e32 v154, v154, v73
	v_add_f32_e32 v154, v154, v57
	v_add_f32_e32 v154, v154, v41
	v_add_f32_e32 v154, v154, v25
	v_add_f32_e32 v154, v154, v9
	s_waitcnt lgkmcnt(0)
	ds_bpermute_b32 v155, v150, v154
	s_waitcnt lgkmcnt(0)
	v_add_f32_e32 v154, v154, v155
	ds_bpermute_b32 v155, v151, v154
	s_waitcnt lgkmcnt(0)
	v_add_f32_e32 v154, v154, v155
	ds_bpermute_b32 v155, v152, v154
	s_waitcnt lgkmcnt(0)
	v_add_f32_e32 v154, v154, v155
	ds_bpermute_b32 v155, v153, v154
	s_and_saveexec_b64 s[62:63], vcc
	s_cbranch_execz .LBB0_216
	s_waitcnt lgkmcnt(0)
	v_add_f32_e32 v154, v154, v155
	global_store_dword v[148:149], v154, off offset:140 nt
	s_bitset1_b32 s98, 11
.LBB0_216:
	s_or_b64 exec, exec, s[62:63]
	v_add_f32_e32 v154, 0, v114
	v_add_f32_e32 v154, v154, v98
	v_add_f32_e32 v154, v154, v82
	v_add_f32_e32 v154, v154, v66
	v_add_f32_e32 v154, v154, v50
	v_add_f32_e32 v154, v154, v34
	v_add_f32_e32 v154, v154, v18
	v_add_f32_e32 v154, v154, v2
	s_waitcnt lgkmcnt(0)
	ds_bpermute_b32 v155, v150, v154
	s_waitcnt lgkmcnt(0)
	v_add_f32_e32 v154, v154, v155
	ds_bpermute_b32 v155, v151, v154
	s_waitcnt lgkmcnt(0)
	v_add_f32_e32 v154, v154, v155
	ds_bpermute_b32 v155, v152, v154
	s_waitcnt lgkmcnt(0)
	v_add_f32_e32 v154, v154, v155
	ds_bpermute_b32 v155, v153, v154
	s_and_saveexec_b64 s[62:63], vcc
	s_cbranch_execz .LBB0_218
	s_waitcnt lgkmcnt(0)
	v_add_f32_e32 v154, v154, v155
	global_store_dword v[148:149], v154, off offset:144 nt
	s_bitset1_b32 s98, 12
.LBB0_218:
	s_or_b64 exec, exec, s[62:63]
	v_add_f32_e32 v154, 0, v115
	v_add_f32_e32 v154, v154, v99
	v_add_f32_e32 v154, v154, v83
	v_add_f32_e32 v154, v154, v67
	v_add_f32_e32 v154, v154, v51
	v_add_f32_e32 v154, v154, v35
	v_add_f32_e32 v154, v154, v19
	v_add_f32_e32 v154, v154, v3
	s_waitcnt lgkmcnt(0)
	ds_bpermute_b32 v155, v150, v154
	s_waitcnt lgkmcnt(0)
	v_add_f32_e32 v154, v154, v155
	ds_bpermute_b32 v155, v151, v154
	s_waitcnt lgkmcnt(0)
	v_add_f32_e32 v154, v154, v155
	ds_bpermute_b32 v155, v152, v154
	s_waitcnt lgkmcnt(0)
	v_add_f32_e32 v154, v154, v155
	ds_bpermute_b32 v155, v153, v154
	s_and_saveexec_b64 s[62:63], vcc
	s_cbranch_execz .LBB0_220
	s_waitcnt lgkmcnt(0)
	v_add_f32_e32 v154, v154, v155
	global_store_dword v[148:149], v154, off offset:148 nt
	s_bitset1_b32 s98, 13
.LBB0_220:
	s_or_b64 exec, exec, s[62:63]
	v_add_f32_e32 v154, 0, v116
	v_add_f32_e32 v154, v154, v100
	v_add_f32_e32 v154, v154, v84
	v_add_f32_e32 v154, v154, v68
	v_add_f32_e32 v154, v154, v52
	v_add_f32_e32 v154, v154, v36
	v_add_f32_e32 v154, v154, v20
	v_add_f32_e32 v154, v154, v4
	s_waitcnt lgkmcnt(0)
	ds_bpermute_b32 v155, v150, v154
	s_waitcnt lgkmcnt(0)
	v_add_f32_e32 v154, v154, v155
	ds_bpermute_b32 v155, v151, v154
	s_waitcnt lgkmcnt(0)
	v_add_f32_e32 v154, v154, v155
	ds_bpermute_b32 v155, v152, v154
	s_waitcnt lgkmcnt(0)
	v_add_f32_e32 v154, v154, v155
	ds_bpermute_b32 v155, v153, v154
	s_and_saveexec_b64 s[62:63], vcc
	s_cbranch_execz .LBB0_222
	s_waitcnt lgkmcnt(0)
	v_add_f32_e32 v154, v154, v155
	global_store_dword v[148:149], v154, off offset:152 nt
	s_bitset1_b32 s98, 14
.LBB0_222:
	s_or_b64 exec, exec, s[62:63]
	v_add_f32_e32 v154, 0, v117
	v_add_f32_e32 v154, v154, v101
	v_add_f32_e32 v154, v154, v85
	v_add_f32_e32 v154, v154, v69
	v_add_f32_e32 v154, v154, v53
	v_add_f32_e32 v154, v154, v37
	v_add_f32_e32 v154, v154, v21
	v_add_f32_e32 v154, v154, v5
	ds_bpermute_b32 v150, v150, v154
	s_waitcnt lgkmcnt(0)
	v_add_f32_e32 v150, v154, v150
	ds_bpermute_b32 v151, v151, v150
	s_waitcnt lgkmcnt(0)
	v_add_f32_e32 v150, v150, v151
	ds_bpermute_b32 v151, v152, v150
	s_waitcnt lgkmcnt(0)
	v_add_f32_e32 v150, v150, v151
	ds_bpermute_b32 v151, v153, v150
	s_and_saveexec_b64 s[62:63], vcc
	s_cbranch_execz .LBB0_224
	s_waitcnt lgkmcnt(0)
	v_add_f32_e32 v150, v150, v151
	global_store_dword v[148:149], v150, off offset:156 nt
	s_bitset1_b32 s98, 15

.LBB0_239:
	s_lshl_b64 s[6:7], s[64:65], 1
	s_add_u32 s6, s14, s6
	s_addc_u32 s7, s15, s7
	s_lshl_b32 s4, s4, 8
	s_add_i32 s4, s4, s76
	v_and_or_b32 v114, v138, 7, s4
	v_mad_i64_i32 v[114:115], s[4:5], s60, v114, 0
	v_lshl_add_u64 v[114:115], v[114:115], 1, s[6:7]
	v_cmp_gt_i32_e64 s[4:5], 8, v138
	v_lshl_add_u64 v[114:115], s[8:9], 1, v[114:115]
	v_lshlrev_b32_e32 v116, 4, v163
	v_cndmask_b32_e64 v138, 64, 0, s[4:5]
	v_lshl_add_u64 v[114:115], v[114:115], 0, v[138:139]
	v_ashrrev_i32_e32 v117, 31, v116
	v_lshl_add_u64 v[152:153], v[114:115], 0, v[116:117]
	v_mov_b32_e32 v114, v139
	v_mov_b32_e32 v115, v139
	v_mov_b32_e32 v116, v139
	v_mov_b32_e32 v117, v139
	v_cvt_pk_bf16_f32 v118, v122, v123
	v_cvt_pk_bf16_f32 v119, v126, v127
	v_cvt_pk_bf16_f32 v120, v124, v125
	v_cvt_pk_bf16_f32 v121, v128, v129
	v_mov_b32_e32 v122, v139
	v_mov_b32_e32 v123, v139
	v_mov_b32_dpp v114, v118 row_ror:8 row_mask:0xf bank_mask:0xf
	v_mov_b32_dpp v115, v119 row_ror:8 row_mask:0xf bank_mask:0xf
	v_mov_b32_e32 v124, v139
	v_mov_b32_dpp v116, v120 row_ror:8 row_mask:0xf bank_mask:0xf
	v_mov_b32_e32 v125, v139
	v_mov_b32_dpp v117, v121 row_ror:8 row_mask:0xf bank_mask:0xf
	s_lshl_b32 s8, s60, 4
	v_mov_b32_dpp v122, v148 row_ror:8 row_mask:0xf bank_mask:0xf
	v_mov_b32_dpp v123, v149 row_ror:8 row_mask:0xf bank_mask:0xf
	v_mov_b32_dpp v124, v150 row_ror:8 row_mask:0xf bank_mask:0xf
	v_mov_b32_dpp v125, v151 row_ror:8 row_mask:0xf bank_mask:0xf
	v_cndmask_b32_e64 v114, v114, v148, s[4:5]
	v_cndmask_b32_e64 v115, v115, v149, s[4:5]
	v_cndmask_b32_e64 v116, v116, v150, s[4:5]
	v_cndmask_b32_e64 v117, v117, v151, s[4:5]
	v_cndmask_b32_e64 v118, v118, v122, s[4:5]
	v_cndmask_b32_e64 v119, v119, v123, s[4:5]
	v_cndmask_b32_e64 v120, v120, v124, s[4:5]
	v_cndmask_b32_e64 v121, v121, v125, s[4:5]
	global_store_dwordx4 v[152:153], v[114:117], off nt
	s_bitset1_b32 s98, 16
	s_cmp_lt_i32 s49, 2
	s_mov_b64 s[62:63], -1
	v_lshl_add_u64 v[114:115], v[152:153], 0, s[8:9]
	global_store_dwordx4 v[114:115], v[118:121], off nt
	s_bitset1_b32 s98, 17
	s_cbranch_scc1 .LBB0_245
	s_cmp_gt_i32 s49, 2
	s_cbranch_scc0 .LBB0_242
	v_mul_f32_e32 v117, 0xbfb8aa3b, v106
	v_mul_f32_e32 v118, 0xbfb8aa3b, v111
	v_exp_f32_e32 v117, v117
	v_exp_f32_e32 v119, v118
	v_mul_f32_e32 v118, 0xbfb8aa3b, v107
	v_exp_f32_e32 v120, v118
	v_add_f32_e32 v117, 1.0, v117
	v_mul_f32_e32 v121, 0xbfb8aa3b, v108
	v_mul_f32_e32 v122, 0xbfb8aa3b, v113
	v_mul_f32_e32 v116, 0xbfb8aa3b, v110
	v_rcp_f32_e32 v118, v117
	v_add_f32_e32 v117, 1.0, v119
	v_add_f32_e32 v119, 1.0, v120
	v_mul_f32_e32 v120, 0xbfb8aa3b, v112
	v_exp_f32_e32 v121, v121
	v_exp_f32_e32 v123, v122
	v_mul_f32_e32 v122, 0xbfb8aa3b, v109
	v_exp_f32_e32 v116, v116
	v_exp_f32_e32 v120, v120
	v_exp_f32_e32 v124, v122
	v_add_f32_e32 v121, 1.0, v121
	v_add_f32_e32 v116, 1.0, v116
	v_add_f32_e32 v120, 1.0, v120
	v_rcp_f32_e32 v122, v121
	v_add_f32_e32 v121, 1.0, v123
	v_add_f32_e32 v123, 1.0, v124
	v_rcp_f32_e32 v116, v116
	v_rcp_f32_e32 v117, v117
	v_rcp_f32_e32 v119, v119
	v_rcp_f32_e32 v120, v120
	v_rcp_f32_e32 v121, v121
	v_rcp_f32_e32 v123, v123
	s_mov_b64 s[62:63], 0

.LBB0_259:
	v_mov_b32_e32 v100, v139
	v_mov_b32_e32 v101, v139
	v_mov_b32_e32 v102, v139
	v_mov_b32_e32 v103, v139
	v_cvt_pk_bf16_f32 v104, v106, v107
	v_cvt_pk_bf16_f32 v105, v110, v111
	v_cvt_pk_bf16_f32 v106, v108, v109
	v_cvt_pk_bf16_f32 v107, v112, v113
	v_mov_b32_e32 v108, v139
	v_mov_b32_e32 v109, v139
	v_mov_b32_dpp v100, v104 row_ror:8 row_mask:0xf bank_mask:0xf
	v_mov_b32_dpp v101, v105 row_ror:8 row_mask:0xf bank_mask:0xf
	v_mov_b32_e32 v110, v139
	v_mov_b32_dpp v102, v106 row_ror:8 row_mask:0xf bank_mask:0xf
	v_mov_b32_e32 v111, v139
	v_mov_b32_dpp v103, v107 row_ror:8 row_mask:0xf bank_mask:0xf
	v_lshl_add_u64 v[98:99], v[114:115], 0, s[8:9]
	v_mov_b32_dpp v108, v116 row_ror:8 row_mask:0xf bank_mask:0xf
	v_mov_b32_dpp v109, v117 row_ror:8 row_mask:0xf bank_mask:0xf
	v_mov_b32_dpp v110, v118 row_ror:8 row_mask:0xf bank_mask:0xf
	v_mov_b32_dpp v111, v119 row_ror:8 row_mask:0xf bank_mask:0xf
	v_cndmask_b32_e64 v100, v100, v116, s[4:5]
	v_cndmask_b32_e64 v101, v101, v117, s[4:5]
	v_cndmask_b32_e64 v102, v102, v118, s[4:5]
	v_cndmask_b32_e64 v103, v103, v119, s[4:5]
	v_cndmask_b32_e64 v104, v104, v108, s[4:5]
	v_cndmask_b32_e64 v105, v105, v109, s[4:5]
	v_cndmask_b32_e64 v106, v106, v110, s[4:5]
	v_cndmask_b32_e64 v107, v107, v111, s[4:5]
	global_store_dwordx4 v[98:99], v[100:103], off nt
	s_bitset1_b32 s98, 18
	s_cmp_lt_i32 s49, 2
	s_mov_b64 s[62:63], -1
	v_lshl_add_u64 v[100:101], v[98:99], 0, s[8:9]
	global_store_dwordx4 v[100:101], v[104:107], off nt
	s_bitset1_b32 s98, 19
	s_cbranch_scc1 .LBB0_265
	s_cmp_gt_i32 s49, 2
	s_cbranch_scc0 .LBB0_262
	v_mul_f32_e32 v101, 0xbfb8aa3b, v90
	v_mul_f32_e32 v102, 0xbfb8aa3b, v95
	v_exp_f32_e32 v101, v101
	v_exp_f32_e32 v103, v102
	v_mul_f32_e32 v102, 0xbfb8aa3b, v91
	v_exp_f32_e32 v104, v102
	v_add_f32_e32 v101, 1.0, v101
	v_mul_f32_e32 v105, 0xbfb8aa3b, v92
	v_mul_f32_e32 v106, 0xbfb8aa3b, v97
	v_mul_f32_e32 v100, 0xbfb8aa3b, v94
	v_rcp_f32_e32 v102, v101
	v_add_f32_e32 v101, 1.0, v103
	v_add_f32_e32 v103, 1.0, v104
	v_mul_f32_e32 v104, 0xbfb8aa3b, v96
	v_exp_f32_e32 v105, v105
	v_exp_f32_e32 v107, v106
	v_mul_f32_e32 v106, 0xbfb8aa3b, v93
	v_exp_f32_e32 v100, v100
	v_exp_f32_e32 v104, v104
	v_exp_f32_e32 v108, v106
	v_add_f32_e32 v105, 1.0, v105
	v_add_f32_e32 v100, 1.0, v100
	v_add_f32_e32 v104, 1.0, v104
	v_rcp_f32_e32 v106, v105
	v_add_f32_e32 v105, 1.0, v107
	v_add_f32_e32 v107, 1.0, v108
	v_rcp_f32_e32 v100, v100
	v_rcp_f32_e32 v101, v101
	v_rcp_f32_e32 v103, v103
	v_rcp_f32_e32 v104, v104
	v_rcp_f32_e32 v105, v105
	v_rcp_f32_e32 v107, v107
	s_mov_b64 s[62:63], 0

.LBB0_279:
	v_mov_b32_e32 v84, v139
	v_mov_b32_e32 v85, v139
	v_mov_b32_e32 v86, v139
	v_mov_b32_e32 v87, v139
	v_cvt_pk_bf16_f32 v88, v90, v91
	v_cvt_pk_bf16_f32 v89, v94, v95
	v_cvt_pk_bf16_f32 v90, v92, v93
	v_cvt_pk_bf16_f32 v91, v96, v97
	s_lshl_b32 s62, s60, 5
	s_mov_b32 s63, s9
	v_mov_b32_e32 v92, v139
	v_mov_b32_dpp v84, v88 row_ror:8 row_mask:0xf bank_mask:0xf
	v_mov_b32_e32 v93, v139
	v_mov_b32_dpp v85, v89 row_ror:8 row_mask:0xf bank_mask:0xf
	v_mov_b32_e32 v94, v139
	v_mov_b32_dpp v86, v90 row_ror:8 row_mask:0xf bank_mask:0xf
	v_mov_b32_e32 v95, v139
	v_mov_b32_dpp v87, v91 row_ror:8 row_mask:0xf bank_mask:0xf
	v_lshl_add_u64 v[82:83], v[98:99], 0, s[62:63]
	v_mov_b32_dpp v92, v100 row_ror:8 row_mask:0xf bank_mask:0xf
	v_mov_b32_dpp v93, v101 row_ror:8 row_mask:0xf bank_mask:0xf
	v_mov_b32_dpp v94, v102 row_ror:8 row_mask:0xf bank_mask:0xf
	v_mov_b32_dpp v95, v103 row_ror:8 row_mask:0xf bank_mask:0xf
	v_cndmask_b32_e64 v84, v84, v100, s[4:5]
	v_cndmask_b32_e64 v85, v85, v101, s[4:5]
	v_cndmask_b32_e64 v86, v86, v102, s[4:5]
	v_cndmask_b32_e64 v87, v87, v103, s[4:5]
	v_cndmask_b32_e64 v88, v88, v92, s[4:5]
	v_cndmask_b32_e64 v89, v89, v93, s[4:5]
	v_cndmask_b32_e64 v90, v90, v94, s[4:5]
	v_cndmask_b32_e64 v91, v91, v95, s[4:5]
	global_store_dwordx4 v[82:83], v[84:87], off nt
	s_bitset1_b32 s98, 20
	s_cmp_lt_i32 s49, 2
	s_mov_b64 s[64:65], -1
	v_lshl_add_u64 v[84:85], v[82:83], 0, s[8:9]
	global_store_dwordx4 v[84:85], v[88:91], off nt
	s_bitset1_b32 s98, 21
	s_cbranch_scc1 .LBB0_285
	s_cmp_gt_i32 s49, 2
	s_cbranch_scc0 .LBB0_282
	v_mul_f32_e32 v85, 0xbfb8aa3b, v74
	v_mul_f32_e32 v86, 0xbfb8aa3b, v79
	v_exp_f32_e32 v85, v85
	v_exp_f32_e32 v87, v86
	v_mul_f32_e32 v86, 0xbfb8aa3b, v75
	v_exp_f32_e32 v88, v86
	v_add_f32_e32 v85, 1.0, v85
	v_mul_f32_e32 v89, 0xbfb8aa3b, v76
	v_mul_f32_e32 v90, 0xbfb8aa3b, v81
	v_mul_f32_e32 v84, 0xbfb8aa3b, v78
	v_rcp_f32_e32 v86, v85
	v_add_f32_e32 v85, 1.0, v87
	v_add_f32_e32 v87, 1.0, v88
	v_mul_f32_e32 v88, 0xbfb8aa3b, v80
	v_exp_f32_e32 v89, v89
	v_exp_f32_e32 v91, v90
	v_mul_f32_e32 v90, 0xbfb8aa3b, v77
	v_exp_f32_e32 v84, v84
	v_exp_f32_e32 v88, v88
	v_exp_f32_e32 v92, v90
	v_add_f32_e32 v89, 1.0, v89
	v_add_f32_e32 v84, 1.0, v84
	v_add_f32_e32 v88, 1.0, v88
	v_rcp_f32_e32 v90, v89
	v_add_f32_e32 v89, 1.0, v91
	v_add_f32_e32 v91, 1.0, v92
	v_rcp_f32_e32 v84, v84
	v_rcp_f32_e32 v85, v85
	v_rcp_f32_e32 v87, v87
	v_rcp_f32_e32 v88, v88
	v_rcp_f32_e32 v89, v89
	v_rcp_f32_e32 v91, v91
	s_mov_b64 s[64:65], 0

.LBB0_299:
	v_mov_b32_e32 v68, v139
	v_mov_b32_e32 v69, v139
	v_mov_b32_e32 v70, v139
	v_mov_b32_e32 v71, v139
	v_cvt_pk_bf16_f32 v72, v74, v75
	v_cvt_pk_bf16_f32 v73, v78, v79
	v_cvt_pk_bf16_f32 v74, v76, v77
	v_cvt_pk_bf16_f32 v75, v80, v81
	v_mov_b32_e32 v76, v139
	v_mov_b32_e32 v77, v139
	v_mov_b32_dpp v68, v72 row_ror:8 row_mask:0xf bank_mask:0xf
	v_mov_b32_dpp v69, v73 row_ror:8 row_mask:0xf bank_mask:0xf
	v_mov_b32_e32 v78, v139
	v_mov_b32_dpp v70, v74 row_ror:8 row_mask:0xf bank_mask:0xf
	v_mov_b32_e32 v79, v139
	v_mov_b32_dpp v71, v75 row_ror:8 row_mask:0xf bank_mask:0xf
	v_lshl_add_u64 v[66:67], v[82:83], 0, s[62:63]
	v_mov_b32_dpp v76, v84 row_ror:8 row_mask:0xf bank_mask:0xf
	v_mov_b32_dpp v77, v85 row_ror:8 row_mask:0xf bank_mask:0xf
	v_mov_b32_dpp v78, v86 row_ror:8 row_mask:0xf bank_mask:0xf
	v_mov_b32_dpp v79, v87 row_ror:8 row_mask:0xf bank_mask:0xf
	v_cndmask_b32_e64 v68, v68, v84, s[4:5]
	v_cndmask_b32_e64 v69, v69, v85, s[4:5]
	v_cndmask_b32_e64 v70, v70, v86, s[4:5]
	v_cndmask_b32_e64 v71, v71, v87, s[4:5]
	v_cndmask_b32_e64 v72, v72, v76, s[4:5]
	v_cndmask_b32_e64 v73, v73, v77, s[4:5]
	v_cndmask_b32_e64 v74, v74, v78, s[4:5]
	v_cndmask_b32_e64 v75, v75, v79, s[4:5]
	global_store_dwordx4 v[66:67], v[68:71], off nt
	s_bitset1_b32 s98, 22
	s_cmp_lt_i32 s49, 2
	s_mov_b64 s[64:65], -1
	v_lshl_add_u64 v[68:69], v[66:67], 0, s[8:9]
	global_store_dwordx4 v[68:69], v[72:75], off nt
	s_bitset1_b32 s98, 23
	s_cbranch_scc1 .LBB0_305
	s_cmp_gt_i32 s49, 2
	s_cbranch_scc0 .LBB0_302
	v_mul_f32_e32 v69, 0xbfb8aa3b, v58
	v_mul_f32_e32 v70, 0xbfb8aa3b, v63
	v_exp_f32_e32 v69, v69
	v_exp_f32_e32 v71, v70
	v_mul_f32_e32 v70, 0xbfb8aa3b, v59
	v_exp_f32_e32 v72, v70
	v_add_f32_e32 v69, 1.0, v69
	v_mul_f32_e32 v73, 0xbfb8aa3b, v60
	v_mul_f32_e32 v74, 0xbfb8aa3b, v65
	v_mul_f32_e32 v68, 0xbfb8aa3b, v62
	v_rcp_f32_e32 v70, v69
	v_add_f32_e32 v69, 1.0, v71
	v_add_f32_e32 v71, 1.0, v72
	v_mul_f32_e32 v72, 0xbfb8aa3b, v64
	v_exp_f32_e32 v73, v73
	v_exp_f32_e32 v75, v74
	v_mul_f32_e32 v74, 0xbfb8aa3b, v61
	v_exp_f32_e32 v68, v68
	v_exp_f32_e32 v72, v72
	v_exp_f32_e32 v76, v74
	v_add_f32_e32 v73, 1.0, v73
	v_add_f32_e32 v68, 1.0, v68
	v_add_f32_e32 v72, 1.0, v72
	v_rcp_f32_e32 v74, v73
	v_add_f32_e32 v73, 1.0, v75
	v_add_f32_e32 v75, 1.0, v76
	v_rcp_f32_e32 v68, v68
	v_rcp_f32_e32 v69, v69
	v_rcp_f32_e32 v71, v71
	v_rcp_f32_e32 v72, v72
	v_rcp_f32_e32 v73, v73
	v_rcp_f32_e32 v75, v75
	s_mov_b64 s[64:65], 0

.LBB0_319:
	v_mov_b32_e32 v52, v139
	v_mov_b32_e32 v53, v139
	v_mov_b32_e32 v54, v139
	v_mov_b32_e32 v55, v139
	v_cvt_pk_bf16_f32 v56, v58, v59
	v_cvt_pk_bf16_f32 v57, v62, v63
	v_cvt_pk_bf16_f32 v58, v60, v61
	v_cvt_pk_bf16_f32 v59, v64, v65
	s_mul_i32 s6, s60, 0xa0
	s_mov_b32 s7, s9
	v_mov_b32_e32 v60, v139
	v_mov_b32_dpp v52, v56 row_ror:8 row_mask:0xf bank_mask:0xf
	v_mov_b32_e32 v61, v139
	v_mov_b32_dpp v53, v57 row_ror:8 row_mask:0xf bank_mask:0xf
	v_mov_b32_e32 v62, v139
	v_mov_b32_dpp v54, v58 row_ror:8 row_mask:0xf bank_mask:0xf
	v_mov_b32_e32 v63, v139
	v_mov_b32_dpp v55, v59 row_ror:8 row_mask:0xf bank_mask:0xf
	v_lshl_add_u64 v[50:51], v[66:67], 0, s[6:7]
	v_mov_b32_dpp v60, v68 row_ror:8 row_mask:0xf bank_mask:0xf
	v_mov_b32_dpp v61, v69 row_ror:8 row_mask:0xf bank_mask:0xf
	v_mov_b32_dpp v62, v70 row_ror:8 row_mask:0xf bank_mask:0xf
	v_mov_b32_dpp v63, v71 row_ror:8 row_mask:0xf bank_mask:0xf
	v_cndmask_b32_e64 v52, v52, v68, s[4:5]
	v_cndmask_b32_e64 v53, v53, v69, s[4:5]
	v_cndmask_b32_e64 v54, v54, v70, s[4:5]
	v_cndmask_b32_e64 v55, v55, v71, s[4:5]
	v_cndmask_b32_e64 v56, v56, v60, s[4:5]
	v_cndmask_b32_e64 v57, v57, v61, s[4:5]
	v_cndmask_b32_e64 v58, v58, v62, s[4:5]
	v_cndmask_b32_e64 v59, v59, v63, s[4:5]
	global_store_dwordx4 v[50:51], v[52:55], off nt
	s_bitset1_b32 s98, 24
	s_cmp_lt_i32 s49, 2
	s_mov_b64 s[60:61], -1
	v_lshl_add_u64 v[52:53], v[50:51], 0, s[8:9]
	global_store_dwordx4 v[52:53], v[56:59], off nt
	s_bitset1_b32 s98, 25
	s_cbranch_scc1 .LBB0_325
	s_cmp_gt_i32 s49, 2
	s_cbranch_scc0 .LBB0_322
	v_mul_f32_e32 v53, 0xbfb8aa3b, v42
	v_mul_f32_e32 v54, 0xbfb8aa3b, v47
	v_exp_f32_e32 v53, v53
	v_exp_f32_e32 v55, v54
	v_mul_f32_e32 v54, 0xbfb8aa3b, v43
	v_exp_f32_e32 v56, v54
	v_add_f32_e32 v53, 1.0, v53
	v_mul_f32_e32 v57, 0xbfb8aa3b, v44
	v_mul_f32_e32 v58, 0xbfb8aa3b, v49
	v_mul_f32_e32 v52, 0xbfb8aa3b, v46
	v_rcp_f32_e32 v54, v53
	v_add_f32_e32 v53, 1.0, v55
	v_add_f32_e32 v55, 1.0, v56
	v_mul_f32_e32 v56, 0xbfb8aa3b, v48
	v_exp_f32_e32 v57, v57
	v_exp_f32_e32 v59, v58
	v_mul_f32_e32 v58, 0xbfb8aa3b, v45
	v_exp_f32_e32 v52, v52
	v_exp_f32_e32 v56, v56
	v_exp_f32_e32 v60, v58
	v_add_f32_e32 v57, 1.0, v57
	v_add_f32_e32 v52, 1.0, v52
	v_add_f32_e32 v56, 1.0, v56
	v_rcp_f32_e32 v58, v57
	v_add_f32_e32 v57, 1.0, v59
	v_add_f32_e32 v59, 1.0, v60
	v_rcp_f32_e32 v52, v52
	v_rcp_f32_e32 v53, v53
	v_rcp_f32_e32 v55, v55
	v_rcp_f32_e32 v56, v56
	v_rcp_f32_e32 v57, v57
	v_rcp_f32_e32 v59, v59
	s_mov_b64 s[60:61], 0

.LBB0_339:
	v_mov_b32_e32 v36, v139
	v_mov_b32_e32 v37, v139
	v_mov_b32_e32 v38, v139
	v_mov_b32_e32 v39, v139
	v_cvt_pk_bf16_f32 v40, v42, v43
	v_cvt_pk_bf16_f32 v41, v46, v47
	v_cvt_pk_bf16_f32 v42, v44, v45
	v_cvt_pk_bf16_f32 v43, v48, v49
	v_mov_b32_e32 v44, v139
	v_mov_b32_e32 v45, v139
	v_mov_b32_dpp v36, v40 row_ror:8 row_mask:0xf bank_mask:0xf
	v_mov_b32_dpp v37, v41 row_ror:8 row_mask:0xf bank_mask:0xf
	v_mov_b32_e32 v46, v139
	v_mov_b32_dpp v38, v42 row_ror:8 row_mask:0xf bank_mask:0xf
	v_mov_b32_e32 v47, v139
	v_mov_b32_dpp v39, v43 row_ror:8 row_mask:0xf bank_mask:0xf
	v_lshl_add_u64 v[34:35], v[50:51], 0, s[62:63]
	v_mov_b32_dpp v44, v52 row_ror:8 row_mask:0xf bank_mask:0xf
	v_mov_b32_dpp v45, v53 row_ror:8 row_mask:0xf bank_mask:0xf
	v_mov_b32_dpp v46, v54 row_ror:8 row_mask:0xf bank_mask:0xf
	v_mov_b32_dpp v47, v55 row_ror:8 row_mask:0xf bank_mask:0xf
	v_cndmask_b32_e64 v36, v36, v52, s[4:5]
	v_cndmask_b32_e64 v37, v37, v53, s[4:5]
	v_cndmask_b32_e64 v38, v38, v54, s[4:5]
	v_cndmask_b32_e64 v39, v39, v55, s[4:5]
	v_cndmask_b32_e64 v40, v40, v44, s[4:5]
	v_cndmask_b32_e64 v41, v41, v45, s[4:5]
	v_cndmask_b32_e64 v42, v42, v46, s[4:5]
	v_cndmask_b32_e64 v43, v43, v47, s[4:5]
	global_store_dwordx4 v[34:35], v[36:39], off nt
	s_bitset1_b32 s98, 26
	s_cmp_lt_i32 s49, 2
	s_mov_b64 s[60:61], -1
	v_lshl_add_u64 v[36:37], v[34:35], 0, s[8:9]
	global_store_dwordx4 v[36:37], v[40:43], off nt
	s_bitset1_b32 s98, 27
	s_cbranch_scc1 .LBB0_345
	s_cmp_gt_i32 s49, 2
	s_cbranch_scc0 .LBB0_342
	v_mul_f32_e32 v37, 0xbfb8aa3b, v26
	v_mul_f32_e32 v38, 0xbfb8aa3b, v31
	v_exp_f32_e32 v37, v37
	v_exp_f32_e32 v39, v38
	v_mul_f32_e32 v38, 0xbfb8aa3b, v27
	v_exp_f32_e32 v40, v38
	v_add_f32_e32 v37, 1.0, v37
	v_mul_f32_e32 v41, 0xbfb8aa3b, v28
	v_mul_f32_e32 v42, 0xbfb8aa3b, v33
	v_mul_f32_e32 v36, 0xbfb8aa3b, v30
	v_rcp_f32_e32 v38, v37
	v_add_f32_e32 v37, 1.0, v39
	v_add_f32_e32 v39, 1.0, v40
	v_mul_f32_e32 v40, 0xbfb8aa3b, v32
	v_exp_f32_e32 v41, v41
	v_exp_f32_e32 v43, v42
	v_mul_f32_e32 v42, 0xbfb8aa3b, v29
	v_exp_f32_e32 v36, v36
	v_exp_f32_e32 v40, v40
	v_exp_f32_e32 v44, v42
	v_add_f32_e32 v41, 1.0, v41
	v_add_f32_e32 v36, 1.0, v36
	v_add_f32_e32 v40, 1.0, v40
	v_rcp_f32_e32 v42, v41
	v_add_f32_e32 v41, 1.0, v43
	v_add_f32_e32 v43, 1.0, v44
	v_rcp_f32_e32 v36, v36
	v_rcp_f32_e32 v37, v37
	v_rcp_f32_e32 v39, v39
	v_rcp_f32_e32 v40, v40
	v_rcp_f32_e32 v41, v41
	v_rcp_f32_e32 v43, v43
	s_mov_b64 s[60:61], 0

.LBB0_359:
	v_mov_b32_e32 v20, v139
	v_mov_b32_e32 v21, v139
	v_mov_b32_e32 v22, v139
	v_mov_b32_e32 v23, v139
	v_cvt_pk_bf16_f32 v24, v26, v27
	v_cvt_pk_bf16_f32 v25, v30, v31
	v_cvt_pk_bf16_f32 v26, v28, v29
	v_cvt_pk_bf16_f32 v27, v32, v33
	v_mov_b32_e32 v28, v139
	v_mov_b32_e32 v29, v139
	v_mov_b32_dpp v20, v24 row_ror:8 row_mask:0xf bank_mask:0xf
	v_mov_b32_dpp v21, v25 row_ror:8 row_mask:0xf bank_mask:0xf
	v_mov_b32_e32 v30, v139
	v_mov_b32_dpp v22, v26 row_ror:8 row_mask:0xf bank_mask:0xf
	v_mov_b32_e32 v31, v139
	v_mov_b32_dpp v23, v27 row_ror:8 row_mask:0xf bank_mask:0xf
	v_lshl_add_u64 v[18:19], v[34:35], 0, s[62:63]
	v_mov_b32_dpp v28, v36 row_ror:8 row_mask:0xf bank_mask:0xf
	v_mov_b32_dpp v29, v37 row_ror:8 row_mask:0xf bank_mask:0xf
	v_mov_b32_dpp v30, v38 row_ror:8 row_mask:0xf bank_mask:0xf
	v_mov_b32_dpp v31, v39 row_ror:8 row_mask:0xf bank_mask:0xf
	v_cndmask_b32_e64 v20, v20, v36, s[4:5]
	v_cndmask_b32_e64 v21, v21, v37, s[4:5]
	v_cndmask_b32_e64 v22, v22, v38, s[4:5]
	v_cndmask_b32_e64 v23, v23, v39, s[4:5]
	v_cndmask_b32_e64 v24, v24, v28, s[4:5]
	v_cndmask_b32_e64 v25, v25, v29, s[4:5]
	v_cndmask_b32_e64 v26, v26, v30, s[4:5]
	v_cndmask_b32_e64 v27, v27, v31, s[4:5]
	global_store_dwordx4 v[18:19], v[20:23], off nt
	s_bitset1_b32 s98, 28
	s_cmp_lt_i32 s49, 2
	s_mov_b64 s[60:61], -1
	v_lshl_add_u64 v[20:21], v[18:19], 0, s[8:9]
	global_store_dwordx4 v[20:21], v[24:27], off nt
	s_bitset1_b32 s98, 29
	s_cbranch_scc1 .LBB0_365
	s_cmp_gt_i32 s49, 2
	s_cbranch_scc0 .LBB0_362
	v_mul_f32_e32 v21, 0xbfb8aa3b, v10
	v_mul_f32_e32 v22, 0xbfb8aa3b, v15
	v_exp_f32_e32 v21, v21
	v_exp_f32_e32 v23, v22
	v_mul_f32_e32 v22, 0xbfb8aa3b, v11
	v_exp_f32_e32 v24, v22
	v_add_f32_e32 v21, 1.0, v21
	v_mul_f32_e32 v25, 0xbfb8aa3b, v12
	v_mul_f32_e32 v26, 0xbfb8aa3b, v17
	v_mul_f32_e32 v20, 0xbfb8aa3b, v14
	v_rcp_f32_e32 v22, v21
	v_add_f32_e32 v21, 1.0, v23
	v_add_f32_e32 v23, 1.0, v24
	v_mul_f32_e32 v24, 0xbfb8aa3b, v16
	v_exp_f32_e32 v25, v25
	v_exp_f32_e32 v27, v26
	v_mul_f32_e32 v26, 0xbfb8aa3b, v13
	v_exp_f32_e32 v20, v20
	v_exp_f32_e32 v24, v24
	v_exp_f32_e32 v28, v26
	v_add_f32_e32 v25, 1.0, v25
	v_add_f32_e32 v20, 1.0, v20
	v_add_f32_e32 v24, 1.0, v24
	v_rcp_f32_e32 v26, v25
	v_add_f32_e32 v25, 1.0, v27
	v_add_f32_e32 v27, 1.0, v28
	v_rcp_f32_e32 v20, v20
	v_rcp_f32_e32 v21, v21
	v_rcp_f32_e32 v23, v23
	v_rcp_f32_e32 v24, v24
	v_rcp_f32_e32 v25, v25
	v_rcp_f32_e32 v27, v27
	s_mov_b64 s[60:61], 0

.LBB0_379:
	v_mov_b32_e32 v2, 0
	v_mov_b32_e32 v3, 0
	v_mov_b32_e32 v4, 0
	v_mov_b32_e32 v5, 0
	v_cvt_pk_bf16_f32 v6, v10, v11
	v_cvt_pk_bf16_f32 v7, v14, v15
	v_cvt_pk_bf16_f32 v8, v12, v13
	v_cvt_pk_bf16_f32 v9, v16, v17
	v_mov_b32_e32 v12, 0
	v_mov_b32_e32 v13, 0
	v_mov_b32_dpp v2, v6 row_ror:8 row_mask:0xf bank_mask:0xf
	v_mov_b32_dpp v3, v7 row_ror:8 row_mask:0xf bank_mask:0xf
	v_mov_b32_e32 v14, 0
	v_mov_b32_dpp v4, v8 row_ror:8 row_mask:0xf bank_mask:0xf
	v_mov_b32_e32 v15, 0
	v_mov_b32_dpp v5, v9 row_ror:8 row_mask:0xf bank_mask:0xf
	v_lshl_add_u64 v[10:11], v[18:19], 0, s[62:63]
	v_mov_b32_dpp v12, v20 row_ror:8 row_mask:0xf bank_mask:0xf
	v_mov_b32_dpp v13, v21 row_ror:8 row_mask:0xf bank_mask:0xf
	v_mov_b32_dpp v14, v22 row_ror:8 row_mask:0xf bank_mask:0xf
	v_mov_b32_dpp v15, v23 row_ror:8 row_mask:0xf bank_mask:0xf
	v_cndmask_b32_e64 v2, v2, v20, s[4:5]
	v_cndmask_b32_e64 v3, v3, v21, s[4:5]
	v_cndmask_b32_e64 v4, v4, v22, s[4:5]
	v_cndmask_b32_e64 v5, v5, v23, s[4:5]
	v_cndmask_b32_e64 v6, v6, v12, s[4:5]
	v_cndmask_b32_e64 v7, v7, v13, s[4:5]
	v_cndmask_b32_e64 v8, v8, v14, s[4:5]
	v_cndmask_b32_e64 v9, v9, v15, s[4:5]
	global_store_dwordx4 v[10:11], v[2:5], off nt
	s_bitset1_b32 s98, 30
	s_andn2_b64 vcc, exec, s[0:1]
	s_mov_b64 s[0:1], -1
	v_lshl_add_u64 v[2:3], v[10:11], 0, s[8:9]
	global_store_dwordx4 v[2:3], v[6:9], off nt
	s_bitset1_b32 s98, 31
	s_cbranch_vccnz .LBB0_171
	s_andn2_b64 vcc, exec, s[12:13]
	s_cbranch_vccnz .LBB0_170
	s_barrier
	s_branch .LBB0_170
.Lrwg1a_relaxed:
	s_cmp_eq_u32 s98, 0xffff0000
	s_cbranch_scc1 .Lrwg1a_c16
	s_cmp_eq_u32 s98, -1
	s_cbranch_scc1 .Lrwg1a_c32
	s_waitcnt vmcnt(8)
	s_branch .Lrwg1a_done
.Lrwg1a_c16:
	s_waitcnt vmcnt(24)
	s_branch .Lrwg1a_done
.Lrwg1a_c32:
	s_waitcnt vmcnt(40)
	s_branch .Lrwg1a_done
.Lrwg1b_relaxed:
	s_cmp_eq_u32 s98, 0xffff0000
	s_cbranch_scc1 .Lrwg1b_c16
	s_cmp_eq_u32 s98, -1
	s_cbranch_scc1 .Lrwg1b_c32
	s_waitcnt vmcnt(8)
	s_mov_b32 s98, 0
	s_branch .Lrwg1b_done
.Lrwg1b_c16:
	s_waitcnt vmcnt(24)
	s_mov_b32 s98, 0
	s_branch .Lrwg1b_done
.Lrwg1b_c32:
	s_waitcnt vmcnt(40)
	s_mov_b32 s98, 0
	s_branch .Lrwg1b_done

.LBB0_770:
	s_mov_b64 s[16:17], 0x80
	s_and_b32 s1, s1, 3
	s_add_i32 m0, s54, 0x18000
	v_lshl_add_u64 v[8:9], v[8:9], 0, s[16:17]
	s_lshl_b32 s59, s7, 6
	s_lshl_b32 s7, s7, 13
	s_lshl_b32 s8, s1, 12
	s_waitcnt vmcnt(2)
	s_barrier
	global_load_lds_dwordx4 v[8:9], off
	v_lshl_add_u64 v[6:7], v[6:7], 0, s[16:17]
	s_add_i32 m0, s54, 0x1a000
	s_add_i32 s60, s54, 0x8000
	s_add_i32 s61, s54, 0xa000
	global_load_lds_dwordx4 v[6:7], off
	v_lshl_add_u64 v[2:3], v[2:3], 0, s[16:17]
	s_mov_b32 m0, s60
	s_add_u32 s36, s50, 0x40080
	global_load_lds_dwordx4 v[2:3], off
	v_lshl_add_u64 v[2:3], v[4:5], 0, s[16:17]
	s_mov_b32 m0, s61
	s_addc_u32 s37, s51, 0
	global_load_lds_dwordx4 v[2:3], off
	s_add_i32 m0, s54, 0x1c000
	v_lshl_add_u64 v[2:3], s[36:37], 0, v[132:133]
	global_load_lds_dwordx4 v[2:3], off
	v_lshl_add_u64 v[2:3], s[36:37], 0, v[136:137]
	s_add_i32 m0, s54, 0x1e000
	v_bfe_u32 v150, v10, 4, 2
	global_load_lds_dwordx4 v[2:3], off
	v_and_b32_e32 v1, 15, v10
	v_lshlrev_b32_e32 v2, 4, v150
	v_lshlrev_b32_e32 v3, 2, v10
	v_lshl_or_b32 v2, v1, 6, v2
	v_and_b32_e32 v3, 32, v3
	v_bitop3_b32 v4, v2, s7, v3 bitop3:0xde
	v_bitop3_b32 v151, v2, s8, v3 bitop3:0xde
	v_lshlrev_b32_e32 v2, 14, v11
	v_and_b32_e32 v2, 0xffff8000, v2
	v_lshl_add_u32 v2, v12, 11, v2
	v_and_b32_e32 v3, 1, v11
	v_lshl_or_b32 v2, v3, 6, v2
	v_lshl_add_u32 v140, v13, 1, v2
	v_lshlrev_b32_e32 v2, 14, v14
	v_and_b32_e32 v2, 0xffff8000, v2
	s_waitcnt vmcnt(6)
	s_cmpk_lt_u32 s6, 0x100
	v_lshl_add_u32 v2, v15, 11, v2
	v_and_b32_e32 v3, 1, v14
	s_sext_i32_i8 s5, s0
	s_cselect_b64 s[36:37], -1, 0
	s_lshl_b32 s0, s1, 6
	v_lshl_or_b32 v2, v3, 6, v2
	s_add_i32 s63, 0, 0x10000
	s_add_i32 s64, 0, 0x14000
	s_ashr_i32 s62, s3, 31
	v_mov_b32_e32 v141, v139
	v_lshl_add_u32 v142, v16, 1, v2
	v_mov_b32_e32 v143, v139
	v_mov_b64_e32 v[144:145], 0x1000
	v_mov_b64_e32 v[146:147], 0xfff
	v_add_u32_e32 v152, s63, v151
	v_add_u32_e32 v153, s64, v151
	v_add_u32_e32 v154, 0, v4
	s_lshl_b32 s8, s0, 1
	s_mov_b32 s65, 0x20000
	s_mov_b32 s66, 0x30000
	s_mov_b32 s67, 0x40000
	s_mov_b32 s68, 0x50000
	s_mov_b32 s69, 0x60000
	s_mov_b32 s70, 0x70000
	s_mov_b32 s71, 0x100000
	s_mov_b32 s72, 0x110000
	s_mov_b32 s73, 0x120000
	s_mov_b32 s74, 0x130000
	s_mov_b32 s75, 0x140000
	s_mov_b32 s76, 0x150000
	s_mov_b32 s98, 0
	s_mov_b32 s77, s9
	s_barrier
	s_waitcnt vmcnt(0)
	s_branch .LBB0_773

.LBB0_780:
	ds_read_b128 v[156:159], v152
	ds_read_b128 v[160:163], v152 offset:1024
	ds_read_b128 v[164:167], v152 offset:2048
	ds_read_b128 v[168:171], v152 offset:3072
	ds_read_b128 v[172:175], v153
	ds_read_b128 v[176:179], v153 offset:1024
	ds_read_b128 v[180:183], v153 offset:2048
	ds_read_b128 v[184:187], v153 offset:3072
	s_add_u32 s6, s48, 0xfffc0080
	s_addc_u32 s7, s49, -1
	s_cmp_eq_u32 s82, 12
	s_cselect_b32 s53, s43, s7
	s_cselect_b32 s52, s78, s6
	s_cselect_b32 s51, s39, s81
	s_cselect_b32 s50, s79, s80
	v_lshl_add_u64 v[148:149], s[48:49], 0, v[140:141]
	s_add_i32 m0, s54, 0xc000
	ds_read_b128 v[188:191], v154
	ds_read_b128 v[192:195], v154 offset:1024
	ds_read_b128 v[196:199], v154 offset:2048
	ds_read_b128 v[200:203], v154 offset:3072
	ds_read_b128 v[204:207], v154 offset:4096
	ds_read_b128 v[208:211], v154 offset:5120
	ds_read_b128 v[212:215], v154 offset:6144
	ds_read_b128 v[216:219], v154 offset:7168
	global_load_lds_dwordx4 v[148:149], off
	v_lshl_add_u64 v[148:149], s[48:49], 0, v[142:143]
	s_add_i32 m0, s54, 0xe000
	s_nop 0
	global_load_lds_dwordx4 v[148:149], off
	s_cmp_lg_u32 s98, 0
	s_cbranch_scc1 .Lrw6a_relaxed
	s_waitcnt vmcnt(8)
.Lrw6a_done:
	s_waitcnt lgkmcnt(0)
	s_barrier
	s_setprio 1
	s_waitcnt lgkmcnt(0)
	v_mfma_f32_16x16x32_bf16 v[126:129], v[156:159], v[188:191], v[126:129]
	v_mfma_f32_16x16x32_bf16 v[122:125], v[164:167], v[188:191], v[122:125]
	v_mfma_f32_16x16x32_bf16 v[110:113], v[156:159], v[196:199], v[110:113]
	v_mfma_f32_16x16x32_bf16 v[106:109], v[164:167], v[196:199], v[106:109]
	v_mfma_f32_16x16x32_bf16 v[94:97], v[156:159], v[204:207], v[94:97]
	v_mfma_f32_16x16x32_bf16 v[90:93], v[164:167], v[204:207], v[90:93]
	v_mfma_f32_16x16x32_bf16 v[78:81], v[156:159], v[212:215], v[78:81]
	v_mfma_f32_16x16x32_bf16 v[74:77], v[164:167], v[212:215], v[74:77]
	v_mfma_f32_16x16x32_bf16 v[126:129], v[160:163], v[192:195], v[126:129]
	v_mfma_f32_16x16x32_bf16 v[122:125], v[168:171], v[192:195], v[122:125]
	v_mfma_f32_16x16x32_bf16 v[110:113], v[160:163], v[200:203], v[110:113]
	v_mfma_f32_16x16x32_bf16 v[106:109], v[168:171], v[200:203], v[106:109]
	v_mfma_f32_16x16x32_bf16 v[94:97], v[160:163], v[208:211], v[94:97]
	v_mfma_f32_16x16x32_bf16 v[90:93], v[168:171], v[208:211], v[90:93]
	v_mfma_f32_16x16x32_bf16 v[78:81], v[160:163], v[216:219], v[78:81]
	v_mfma_f32_16x16x32_bf16 v[74:77], v[168:171], v[216:219], v[74:77]
	s_setprio 0
	s_setprio 1
	v_mfma_f32_16x16x32_bf16 v[118:121], v[172:175], v[188:191], v[118:121]
	v_mfma_f32_16x16x32_bf16 v[114:117], v[180:183], v[188:191], v[114:117]
	v_mfma_f32_16x16x32_bf16 v[102:105], v[172:175], v[196:199], v[102:105]
	v_mfma_f32_16x16x32_bf16 v[98:101], v[180:183], v[196:199], v[98:101]
	v_mfma_f32_16x16x32_bf16 v[86:89], v[172:175], v[204:207], v[86:89]
	v_mfma_f32_16x16x32_bf16 v[82:85], v[180:183], v[204:207], v[82:85]
	v_mfma_f32_16x16x32_bf16 v[70:73], v[172:175], v[212:215], v[70:73]
	v_mfma_f32_16x16x32_bf16 v[66:69], v[180:183], v[212:215], v[66:69]
	v_mfma_f32_16x16x32_bf16 v[118:121], v[176:179], v[192:195], v[118:121]
	v_mfma_f32_16x16x32_bf16 v[114:117], v[184:187], v[192:195], v[114:117]
	v_mfma_f32_16x16x32_bf16 v[102:105], v[176:179], v[200:203], v[102:105]
	v_mfma_f32_16x16x32_bf16 v[98:101], v[184:187], v[200:203], v[98:101]
	v_mfma_f32_16x16x32_bf16 v[86:89], v[176:179], v[208:211], v[86:89]
	v_mfma_f32_16x16x32_bf16 v[82:85], v[184:187], v[208:211], v[82:85]
	v_mfma_f32_16x16x32_bf16 v[70:73], v[176:179], v[216:219], v[70:73]
	v_mfma_f32_16x16x32_bf16 v[66:69], v[184:187], v[216:219], v[66:69]
	s_setprio 0
	s_barrier
	s_add_i32 s6, s63, s31
	v_lshl_add_u64 v[148:149], s[50:51], 0, v[132:133]
	s_mov_b32 m0, s6
	ds_read_b128 v[188:191], v154 offset:16384
	ds_read_b128 v[192:195], v154 offset:17408
	ds_read_b128 v[196:199], v154 offset:18432
	ds_read_b128 v[200:203], v154 offset:19456
	ds_read_b128 v[204:207], v154 offset:20480
	ds_read_b128 v[208:211], v154 offset:21504
	ds_read_b128 v[212:215], v154 offset:22528
	ds_read_b128 v[216:219], v154 offset:23552
	global_load_lds_dwordx4 v[148:149], off
	s_add_i32 m0, s6, 0x2000
	s_add_u32 s6, s50, 0x40000
	v_lshl_add_u64 v[220:221], s[50:51], 0, v[136:137]
	s_addc_u32 s7, s51, 0
	s_add_i32 s83, s64, s31
	global_load_lds_dwordx4 v[220:221], off
	v_lshl_add_u64 v[222:223], s[6:7], 0, v[132:133]
	s_mov_b32 m0, s83
	v_lshl_add_u64 v[224:225], s[52:53], 0, v[134:135]
	global_load_lds_dwordx4 v[222:223], off
	v_lshl_add_u64 v[222:223], s[6:7], 0, v[136:137]
	s_add_i32 m0, s83, 0x2000
	s_nop 0
	global_load_lds_dwordx4 v[222:223], off
	v_lshl_add_u64 v[222:223], s[52:53], 0, v[130:131]
	s_mov_b32 m0, s54
	s_nop 0
	global_load_lds_dwordx4 v[222:223], off
	s_mov_b32 m0, s55
	s_nop 0
	global_load_lds_dwordx4 v[224:225], off
	s_cmp_lg_u32 s98, 0
	s_cbranch_scc1 .Lrw6b_relaxed
	s_waitcnt vmcnt(8)
.Lrw6b_done:
	s_waitcnt lgkmcnt(0)
	s_barrier
	s_setprio 1
	s_waitcnt lgkmcnt(0)
	v_mfma_f32_16x16x32_bf16 v[62:65], v[156:159], v[188:191], v[62:65]
	v_mfma_f32_16x16x32_bf16 v[58:61], v[164:167], v[188:191], v[58:61]
	v_mfma_f32_16x16x32_bf16 v[46:49], v[156:159], v[196:199], v[46:49]
	v_mfma_f32_16x16x32_bf16 v[42:45], v[164:167], v[196:199], v[42:45]
	v_mfma_f32_16x16x32_bf16 v[30:33], v[156:159], v[204:207], v[30:33]
	v_mfma_f32_16x16x32_bf16 v[26:29], v[164:167], v[204:207], v[26:29]
	v_mfma_f32_16x16x32_bf16 v[14:17], v[156:159], v[212:215], v[14:17]
	v_mfma_f32_16x16x32_bf16 v[10:13], v[164:167], v[212:215], v[10:13]
	v_mfma_f32_16x16x32_bf16 v[62:65], v[160:163], v[192:195], v[62:65]
	v_mfma_f32_16x16x32_bf16 v[58:61], v[168:171], v[192:195], v[58:61]
	v_mfma_f32_16x16x32_bf16 v[46:49], v[160:163], v[200:203], v[46:49]
	v_mfma_f32_16x16x32_bf16 v[42:45], v[168:171], v[200:203], v[42:45]
	v_mfma_f32_16x16x32_bf16 v[30:33], v[160:163], v[208:211], v[30:33]
	v_mfma_f32_16x16x32_bf16 v[26:29], v[168:171], v[208:211], v[26:29]
	v_mfma_f32_16x16x32_bf16 v[14:17], v[160:163], v[216:219], v[14:17]
	v_mfma_f32_16x16x32_bf16 v[10:13], v[168:171], v[216:219], v[10:13]
	s_setprio 0
	s_setprio 1
	v_mfma_f32_16x16x32_bf16 v[54:57], v[172:175], v[188:191], v[54:57]
	v_mfma_f32_16x16x32_bf16 v[50:53], v[180:183], v[188:191], v[50:53]
	v_mfma_f32_16x16x32_bf16 v[38:41], v[172:175], v[196:199], v[38:41]
	v_mfma_f32_16x16x32_bf16 v[34:37], v[180:183], v[196:199], v[34:37]
	v_mfma_f32_16x16x32_bf16 v[22:25], v[172:175], v[204:207], v[22:25]
	v_mfma_f32_16x16x32_bf16 v[18:21], v[180:183], v[204:207], v[18:21]
	v_mfma_f32_16x16x32_bf16 v[6:9], v[172:175], v[212:215], v[6:9]
	v_mfma_f32_16x16x32_bf16 v[2:5], v[180:183], v[212:215], v[2:5]
	v_mfma_f32_16x16x32_bf16 v[54:57], v[176:179], v[192:195], v[54:57]
	v_mfma_f32_16x16x32_bf16 v[50:53], v[184:187], v[192:195], v[50:53]
	v_mfma_f32_16x16x32_bf16 v[38:41], v[176:179], v[200:203], v[38:41]
	v_mfma_f32_16x16x32_bf16 v[34:37], v[184:187], v[200:203], v[34:37]
	v_mfma_f32_16x16x32_bf16 v[22:25], v[176:179], v[208:211], v[22:25]
	v_mfma_f32_16x16x32_bf16 v[18:21], v[184:187], v[208:211], v[18:21]
	v_mfma_f32_16x16x32_bf16 v[6:9], v[176:179], v[216:219], v[6:9]
	v_mfma_f32_16x16x32_bf16 v[2:5], v[184:187], v[216:219], v[2:5]
	s_setprio 0
	s_barrier
	s_add_i32 s83, 0, 0x18000
	v_add_u32_e32 v138, s83, v151
	s_add_i32 s84, 0, 0x1c000
	ds_read_b128 v[156:159], v138
	ds_read_b128 v[160:163], v138 offset:1024
	ds_read_b128 v[164:167], v138 offset:2048
	ds_read_b128 v[168:171], v138 offset:3072
	v_add_u32_e32 v138, s84, v151
	ds_read_b128 v[172:175], v138
	ds_read_b128 v[176:179], v138 offset:1024
	ds_read_b128 v[180:183], v138 offset:2048
	ds_read_b128 v[184:187], v138 offset:3072
	s_add_u32 s6, s52, 0x40000
	s_addc_u32 s7, s53, 0
	s_mov_b32 m0, s56
	v_lshl_add_u64 v[226:227], s[6:7], 0, v[130:131]
	ds_read_b128 v[188:191], v154 offset:32768
	ds_read_b128 v[192:195], v154 offset:33792
	ds_read_b128 v[196:199], v154 offset:34816
	ds_read_b128 v[200:203], v154 offset:35840
	ds_read_b128 v[204:207], v154 offset:36864
	ds_read_b128 v[208:211], v154 offset:37888
	ds_read_b128 v[212:215], v154 offset:38912
	ds_read_b128 v[216:219], v154 offset:39936
	global_load_lds_dwordx4 v[226:227], off
	v_lshl_add_u64 v[226:227], s[6:7], 0, v[134:135]
	s_mov_b32 m0, s57
	s_nop 0
	global_load_lds_dwordx4 v[226:227], off
	s_waitcnt vmcnt(8)
	s_waitcnt lgkmcnt(0)
	s_barrier
	s_setprio 1
	s_waitcnt lgkmcnt(0)
	v_mfma_f32_16x16x32_bf16 v[126:129], v[156:159], v[188:191], v[126:129]
	v_mfma_f32_16x16x32_bf16 v[122:125], v[164:167], v[188:191], v[122:125]
	v_mfma_f32_16x16x32_bf16 v[110:113], v[156:159], v[196:199], v[110:113]
	v_mfma_f32_16x16x32_bf16 v[106:109], v[164:167], v[196:199], v[106:109]
	v_mfma_f32_16x16x32_bf16 v[94:97], v[156:159], v[204:207], v[94:97]
	v_mfma_f32_16x16x32_bf16 v[90:93], v[164:167], v[204:207], v[90:93]
	v_mfma_f32_16x16x32_bf16 v[78:81], v[156:159], v[212:215], v[78:81]
	v_mfma_f32_16x16x32_bf16 v[74:77], v[164:167], v[212:215], v[74:77]
	v_mfma_f32_16x16x32_bf16 v[126:129], v[160:163], v[192:195], v[126:129]
	v_mfma_f32_16x16x32_bf16 v[122:125], v[168:171], v[192:195], v[122:125]
	v_mfma_f32_16x16x32_bf16 v[110:113], v[160:163], v[200:203], v[110:113]
	v_mfma_f32_16x16x32_bf16 v[106:109], v[168:171], v[200:203], v[106:109]
	v_mfma_f32_16x16x32_bf16 v[94:97], v[160:163], v[208:211], v[94:97]
	v_mfma_f32_16x16x32_bf16 v[90:93], v[168:171], v[208:211], v[90:93]
	v_mfma_f32_16x16x32_bf16 v[78:81], v[160:163], v[216:219], v[78:81]
	v_mfma_f32_16x16x32_bf16 v[74:77], v[168:171], v[216:219], v[74:77]
	s_setprio 0
	s_setprio 1
	v_mfma_f32_16x16x32_bf16 v[118:121], v[172:175], v[188:191], v[118:121]
	v_mfma_f32_16x16x32_bf16 v[114:117], v[180:183], v[188:191], v[114:117]
	v_mfma_f32_16x16x32_bf16 v[102:105], v[172:175], v[196:199], v[102:105]
	v_mfma_f32_16x16x32_bf16 v[98:101], v[180:183], v[196:199], v[98:101]
	v_mfma_f32_16x16x32_bf16 v[86:89], v[172:175], v[204:207], v[86:89]
	v_mfma_f32_16x16x32_bf16 v[82:85], v[180:183], v[204:207], v[82:85]
	v_mfma_f32_16x16x32_bf16 v[70:73], v[172:175], v[212:215], v[70:73]
	v_mfma_f32_16x16x32_bf16 v[66:69], v[180:183], v[212:215], v[66:69]
	v_mfma_f32_16x16x32_bf16 v[118:121], v[176:179], v[192:195], v[118:121]
	v_mfma_f32_16x16x32_bf16 v[114:117], v[184:187], v[192:195], v[114:117]
	v_mfma_f32_16x16x32_bf16 v[102:105], v[176:179], v[200:203], v[102:105]
	v_mfma_f32_16x16x32_bf16 v[98:101], v[184:187], v[200:203], v[98:101]
	v_mfma_f32_16x16x32_bf16 v[86:89], v[176:179], v[208:211], v[86:89]
	v_mfma_f32_16x16x32_bf16 v[82:85], v[184:187], v[208:211], v[82:85]
	v_mfma_f32_16x16x32_bf16 v[70:73], v[176:179], v[216:219], v[70:73]
	v_mfma_f32_16x16x32_bf16 v[66:69], v[184:187], v[216:219], v[66:69]
	s_setprio 0
	s_barrier
	s_add_i32 s6, s83, s31
	v_lshl_add_u64 v[148:149], v[148:149], 0, s[16:17]
	s_mov_b32 m0, s6
	ds_read_b128 v[188:191], v154 offset:49152
	ds_read_b128 v[192:195], v154 offset:50176
	ds_read_b128 v[196:199], v154 offset:51200
	ds_read_b128 v[200:203], v154 offset:52224
	ds_read_b128 v[204:207], v154 offset:53248
	ds_read_b128 v[208:211], v154 offset:54272
	ds_read_b128 v[212:215], v154 offset:55296
	ds_read_b128 v[216:219], v154 offset:56320
	global_load_lds_dwordx4 v[148:149], off
	s_add_i32 m0, s6, 0x2000
	s_add_u32 s6, s50, 0x40080
	v_lshl_add_u64 v[148:149], v[220:221], 0, s[16:17]
	s_addc_u32 s7, s51, 0
	s_add_i32 s50, s84, s31
	global_load_lds_dwordx4 v[148:149], off
	v_lshl_add_u64 v[148:149], s[6:7], 0, v[132:133]
	s_mov_b32 m0, s50
	s_nop 0
	global_load_lds_dwordx4 v[148:149], off
	v_lshl_add_u64 v[148:149], s[6:7], 0, v[136:137]
	s_add_i32 m0, s50, 0x2000
	s_nop 0
	global_load_lds_dwordx4 v[148:149], off
	v_lshl_add_u64 v[148:149], v[222:223], 0, s[16:17]
	s_mov_b32 m0, s60
	s_nop 0
	global_load_lds_dwordx4 v[148:149], off
	v_lshl_add_u64 v[148:149], v[224:225], 0, s[16:17]
	s_mov_b32 m0, s61
	s_nop 0
	global_load_lds_dwordx4 v[148:149], off
	s_waitcnt vmcnt(8)
	s_waitcnt lgkmcnt(0)
	s_barrier
	s_setprio 1
	s_waitcnt lgkmcnt(0)
	v_mfma_f32_16x16x32_bf16 v[62:65], v[156:159], v[188:191], v[62:65]
	v_mfma_f32_16x16x32_bf16 v[58:61], v[164:167], v[188:191], v[58:61]
	v_mfma_f32_16x16x32_bf16 v[46:49], v[156:159], v[196:199], v[46:49]
	v_mfma_f32_16x16x32_bf16 v[42:45], v[164:167], v[196:199], v[42:45]
	v_mfma_f32_16x16x32_bf16 v[30:33], v[156:159], v[204:207], v[30:33]
	v_mfma_f32_16x16x32_bf16 v[26:29], v[164:167], v[204:207], v[26:29]
	v_mfma_f32_16x16x32_bf16 v[14:17], v[156:159], v[212:215], v[14:17]
	v_mfma_f32_16x16x32_bf16 v[10:13], v[164:167], v[212:215], v[10:13]
	v_mfma_f32_16x16x32_bf16 v[62:65], v[160:163], v[192:195], v[62:65]
	v_mfma_f32_16x16x32_bf16 v[58:61], v[168:171], v[192:195], v[58:61]
	v_mfma_f32_16x16x32_bf16 v[46:49], v[160:163], v[200:203], v[46:49]
	v_mfma_f32_16x16x32_bf16 v[42:45], v[168:171], v[200:203], v[42:45]
	v_mfma_f32_16x16x32_bf16 v[30:33], v[160:163], v[208:211], v[30:33]
	v_mfma_f32_16x16x32_bf16 v[26:29], v[168:171], v[208:211], v[26:29]
	v_mfma_f32_16x16x32_bf16 v[14:17], v[160:163], v[216:219], v[14:17]
	v_mfma_f32_16x16x32_bf16 v[10:13], v[168:171], v[216:219], v[10:13]
	s_setprio 0
	s_setprio 1
	v_mfma_f32_16x16x32_bf16 v[54:57], v[172:175], v[188:191], v[54:57]
	v_mfma_f32_16x16x32_bf16 v[50:53], v[180:183], v[188:191], v[50:53]
	v_mfma_f32_16x16x32_bf16 v[38:41], v[172:175], v[196:199], v[38:41]
	v_mfma_f32_16x16x32_bf16 v[34:37], v[180:183], v[196:199], v[34:37]
	v_mfma_f32_16x16x32_bf16 v[22:25], v[172:175], v[204:207], v[22:25]
	v_mfma_f32_16x16x32_bf16 v[18:21], v[180:183], v[204:207], v[18:21]
	v_mfma_f32_16x16x32_bf16 v[6:9], v[172:175], v[212:215], v[6:9]
	v_mfma_f32_16x16x32_bf16 v[2:5], v[180:183], v[212:215], v[2:5]
	v_mfma_f32_16x16x32_bf16 v[54:57], v[176:179], v[192:195], v[54:57]
	v_mfma_f32_16x16x32_bf16 v[50:53], v[184:187], v[192:195], v[50:53]
	v_mfma_f32_16x16x32_bf16 v[38:41], v[176:179], v[200:203], v[38:41]
	v_mfma_f32_16x16x32_bf16 v[34:37], v[184:187], v[200:203], v[34:37]
	v_mfma_f32_16x16x32_bf16 v[22:25], v[176:179], v[208:211], v[22:25]
	v_mfma_f32_16x16x32_bf16 v[18:21], v[184:187], v[208:211], v[18:21]
	v_mfma_f32_16x16x32_bf16 v[6:9], v[176:179], v[216:219], v[6:9]
	v_mfma_f32_16x16x32_bf16 v[2:5], v[184:187], v[216:219], v[2:5]
	s_setprio 0
	s_barrier
	s_add_i32 s82, s82, 2
	s_add_u32 s48, s48, 0x100
	s_addc_u32 s49, s49, 0
	s_add_u32 s80, s80, 0x100
	s_addc_u32 s81, s81, 0
	s_cmp_gt_u32 s82, 13
	s_cbranch_scc0 .LBB0_780
	s_and_b64 vcc, exec, s[36:37]
	s_cbranch_vccz .LBB0_783
	s_barrier
.LBB0_783:
	s_lshl_b32 s98, s4, 8
	s_add_i32 s98, s98, s59
	s_lshl_b32 s98, s98, 13
	s_lshl_b32 s99, s5, 9
	s_add_u32 s98, s98, s99
	s_add_u32 s98, s98, s8
	s_add_u32 s98, s14, s98
	s_addc_u32 s99, s15, 0
	v_and_b32_e32 v148, 7, v1
	v_lshlrev_b32_e32 v148, 13, v148
	v_lshl_add_u32 v148, v150, 4, v148
	v_and_b32_e32 v149, 8, v1
	v_lshl_add_u32 v148, v149, 3, v148
	v_max_f32_e32 v122, 0, v122
	v_max_f32_e32 v123, 0, v123
	v_max_f32_e32 v124, 0, v124
	v_max_f32_e32 v125, 0, v125
	v_max_f32_e32 v126, 0, v126
	v_max_f32_e32 v127, 0, v127
	v_max_f32_e32 v128, 0, v128
	v_max_f32_e32 v129, 0, v129
	v_max_f32_e32 v114, 0, v114
	v_max_f32_e32 v115, 0, v115
	v_max_f32_e32 v116, 0, v116
	v_max_f32_e32 v117, 0, v117
	v_max_f32_e32 v118, 0, v118
	v_max_f32_e32 v119, 0, v119
	v_max_f32_e32 v120, 0, v120
	v_max_f32_e32 v121, 0, v121
	v_mul_f32_e32 v122, v122, v122
	v_mul_f32_e32 v123, v123, v123
	v_mul_f32_e32 v124, v124, v124
	v_mul_f32_e32 v125, v125, v125
	v_mul_f32_e32 v126, v126, v126
	v_mul_f32_e32 v127, v127, v127
	v_mul_f32_e32 v128, v128, v128
	v_mul_f32_e32 v129, v129, v129
	v_mul_f32_e32 v114, v114, v114
	v_mul_f32_e32 v115, v115, v115
	v_mul_f32_e32 v116, v116, v116
	v_mul_f32_e32 v117, v117, v117
	v_mul_f32_e32 v118, v118, v118
	v_mul_f32_e32 v119, v119, v119
	v_mul_f32_e32 v120, v120, v120
	v_mul_f32_e32 v121, v121, v121
	v_cvt_pk_bf16_f32 v126, v126, v127
	v_cvt_pk_bf16_f32 v127, v128, v129
	v_cvt_pk_bf16_f32 v128, v122, v123
	v_cvt_pk_bf16_f32 v129, v124, v125
	v_cvt_pk_bf16_f32 v118, v118, v119
	v_cvt_pk_bf16_f32 v119, v120, v121
	v_cvt_pk_bf16_f32 v120, v114, v115
	v_cvt_pk_bf16_f32 v121, v116, v117
	v_mov_b32_e32 v122, v126
	v_mov_b32_e32 v123, v127
	v_mov_b32_e32 v124, v128
	v_mov_b32_e32 v125, v129
	v_mov_b32_dpp v126, v118 row_ror:8 row_mask:0xf bank_mask:0xc
	v_mov_b32_dpp v127, v119 row_ror:8 row_mask:0xf bank_mask:0xc
	v_mov_b32_dpp v128, v120 row_ror:8 row_mask:0xf bank_mask:0xc
	v_mov_b32_dpp v129, v121 row_ror:8 row_mask:0xf bank_mask:0xc
	v_mov_b32_dpp v118, v122 row_ror:8 row_mask:0xf bank_mask:0x3
	v_mov_b32_dpp v119, v123 row_ror:8 row_mask:0xf bank_mask:0x3
	v_mov_b32_dpp v120, v124 row_ror:8 row_mask:0xf bank_mask:0x3
	v_mov_b32_dpp v121, v125 row_ror:8 row_mask:0xf bank_mask:0x3
	global_store_dwordx4 v148, v[126:129], s[98:99] nt
	s_add_u32 s98, s98, 0x10000
	s_addc_u32 s99, s99, 0
	global_store_dwordx4 v148, v[118:121], s[98:99] nt
	v_max_f32_e32 v106, 0, v106
	v_max_f32_e32 v107, 0, v107
	v_max_f32_e32 v108, 0, v108
	v_max_f32_e32 v109, 0, v109
	v_max_f32_e32 v110, 0, v110
	v_max_f32_e32 v111, 0, v111
	v_max_f32_e32 v112, 0, v112
	v_max_f32_e32 v113, 0, v113
	v_max_f32_e32 v98, 0, v98
	v_max_f32_e32 v99, 0, v99
	v_max_f32_e32 v100, 0, v100
	v_max_f32_e32 v101, 0, v101
	v_max_f32_e32 v102, 0, v102
	v_max_f32_e32 v103, 0, v103
	v_max_f32_e32 v104, 0, v104
	v_max_f32_e32 v105, 0, v105
	v_mul_f32_e32 v106, v106, v106
	v_mul_f32_e32 v107, v107, v107
	v_mul_f32_e32 v108, v108, v108
	v_mul_f32_e32 v109, v109, v109
	v_mul_f32_e32 v110, v110, v110
	v_mul_f32_e32 v111, v111, v111
	v_mul_f32_e32 v112, v112, v112
	v_mul_f32_e32 v113, v113, v113
	v_mul_f32_e32 v98, v98, v98
	v_mul_f32_e32 v99, v99, v99
	v_mul_f32_e32 v100, v100, v100
	v_mul_f32_e32 v101, v101, v101
	v_mul_f32_e32 v102, v102, v102
	v_mul_f32_e32 v103, v103, v103
	v_mul_f32_e32 v104, v104, v104
	v_mul_f32_e32 v105, v105, v105
	v_cvt_pk_bf16_f32 v110, v110, v111
	v_cvt_pk_bf16_f32 v111, v112, v113
	v_cvt_pk_bf16_f32 v112, v106, v107
	v_cvt_pk_bf16_f32 v113, v108, v109
	v_cvt_pk_bf16_f32 v102, v102, v103
	v_cvt_pk_bf16_f32 v103, v104, v105
	v_cvt_pk_bf16_f32 v104, v98, v99
	v_cvt_pk_bf16_f32 v105, v100, v101
	v_mov_b32_e32 v106, v110
	v_mov_b32_e32 v107, v111
	v_mov_b32_e32 v108, v112
	v_mov_b32_e32 v109, v113
	v_mov_b32_dpp v110, v102 row_ror:8 row_mask:0xf bank_mask:0xc
	v_mov_b32_dpp v111, v103 row_ror:8 row_mask:0xf bank_mask:0xc
	v_mov_b32_dpp v112, v104 row_ror:8 row_mask:0xf bank_mask:0xc
	v_mov_b32_dpp v113, v105 row_ror:8 row_mask:0xf bank_mask:0xc
	v_mov_b32_dpp v102, v106 row_ror:8 row_mask:0xf bank_mask:0x3
	v_mov_b32_dpp v103, v107 row_ror:8 row_mask:0xf bank_mask:0x3
	v_mov_b32_dpp v104, v108 row_ror:8 row_mask:0xf bank_mask:0x3
	v_mov_b32_dpp v105, v109 row_ror:8 row_mask:0xf bank_mask:0x3
	s_add_u32 s98, s98, 0x10000
	s_addc_u32 s99, s99, 0
	global_store_dwordx4 v148, v[110:113], s[98:99] nt
	s_add_u32 s98, s98, 0x10000
	s_addc_u32 s99, s99, 0
	global_store_dwordx4 v148, v[102:105], s[98:99] nt
	v_max_f32_e32 v90, 0, v90
	v_max_f32_e32 v91, 0, v91
	v_max_f32_e32 v92, 0, v92
	v_max_f32_e32 v93, 0, v93
	v_max_f32_e32 v94, 0, v94
	v_max_f32_e32 v95, 0, v95
	v_max_f32_e32 v96, 0, v96
	v_max_f32_e32 v97, 0, v97
	v_max_f32_e32 v82, 0, v82
	v_max_f32_e32 v83, 0, v83
	v_max_f32_e32 v84, 0, v84
	v_max_f32_e32 v85, 0, v85
	v_max_f32_e32 v86, 0, v86
	v_max_f32_e32 v87, 0, v87
	v_max_f32_e32 v88, 0, v88
	v_max_f32_e32 v89, 0, v89
	v_mul_f32_e32 v90, v90, v90
	v_mul_f32_e32 v91, v91, v91
	v_mul_f32_e32 v92, v92, v92
	v_mul_f32_e32 v93, v93, v93
	v_mul_f32_e32 v94, v94, v94
	v_mul_f32_e32 v95, v95, v95
	v_mul_f32_e32 v96, v96, v96
	v_mul_f32_e32 v97, v97, v97
	v_mul_f32_e32 v82, v82, v82
	v_mul_f32_e32 v83, v83, v83
	v_mul_f32_e32 v84, v84, v84
	v_mul_f32_e32 v85, v85, v85
	v_mul_f32_e32 v86, v86, v86
	v_mul_f32_e32 v87, v87, v87
	v_mul_f32_e32 v88, v88, v88
	v_mul_f32_e32 v89, v89, v89
	v_cvt_pk_bf16_f32 v94, v94, v95
	v_cvt_pk_bf16_f32 v95, v96, v97
	v_cvt_pk_bf16_f32 v96, v90, v91
	v_cvt_pk_bf16_f32 v97, v92, v93
	v_cvt_pk_bf16_f32 v86, v86, v87
	v_cvt_pk_bf16_f32 v87, v88, v89
	v_cvt_pk_bf16_f32 v88, v82, v83
	v_cvt_pk_bf16_f32 v89, v84, v85
	v_mov_b32_e32 v90, v94
	v_mov_b32_e32 v91, v95
	v_mov_b32_e32 v92, v96
	v_mov_b32_e32 v93, v97
	v_mov_b32_dpp v94, v86 row_ror:8 row_mask:0xf bank_mask:0xc
	v_mov_b32_dpp v95, v87 row_ror:8 row_mask:0xf bank_mask:0xc
	v_mov_b32_dpp v96, v88 row_ror:8 row_mask:0xf bank_mask:0xc
	v_mov_b32_dpp v97, v89 row_ror:8 row_mask:0xf bank_mask:0xc
	v_mov_b32_dpp v86, v90 row_ror:8 row_mask:0xf bank_mask:0x3
	v_mov_b32_dpp v87, v91 row_ror:8 row_mask:0xf bank_mask:0x3
	v_mov_b32_dpp v88, v92 row_ror:8 row_mask:0xf bank_mask:0x3
	v_mov_b32_dpp v89, v93 row_ror:8 row_mask:0xf bank_mask:0x3
	s_add_u32 s98, s98, 0x10000
	s_addc_u32 s99, s99, 0
	global_store_dwordx4 v148, v[94:97], s[98:99] nt
	s_add_u32 s98, s98, 0x10000
	s_addc_u32 s99, s99, 0
	global_store_dwordx4 v148, v[86:89], s[98:99] nt
	v_max_f32_e32 v74, 0, v74
	v_max_f32_e32 v75, 0, v75
	v_max_f32_e32 v76, 0, v76
	v_max_f32_e32 v77, 0, v77
	v_max_f32_e32 v78, 0, v78
	v_max_f32_e32 v79, 0, v79
	v_max_f32_e32 v80, 0, v80
	v_max_f32_e32 v81, 0, v81
	v_max_f32_e32 v66, 0, v66
	v_max_f32_e32 v67, 0, v67
	v_max_f32_e32 v68, 0, v68
	v_max_f32_e32 v69, 0, v69
	v_max_f32_e32 v70, 0, v70
	v_max_f32_e32 v71, 0, v71
	v_max_f32_e32 v72, 0, v72
	v_max_f32_e32 v73, 0, v73
	v_mul_f32_e32 v74, v74, v74
	v_mul_f32_e32 v75, v75, v75
	v_mul_f32_e32 v76, v76, v76
	v_mul_f32_e32 v77, v77, v77
	v_mul_f32_e32 v78, v78, v78
	v_mul_f32_e32 v79, v79, v79
	v_mul_f32_e32 v80, v80, v80
	v_mul_f32_e32 v81, v81, v81
	v_mul_f32_e32 v66, v66, v66
	v_mul_f32_e32 v67, v67, v67
	v_mul_f32_e32 v68, v68, v68
	v_mul_f32_e32 v69, v69, v69
	v_mul_f32_e32 v70, v70, v70
	v_mul_f32_e32 v71, v71, v71
	v_mul_f32_e32 v72, v72, v72
	v_mul_f32_e32 v73, v73, v73
	v_cvt_pk_bf16_f32 v78, v78, v79
	v_cvt_pk_bf16_f32 v79, v80, v81
	v_cvt_pk_bf16_f32 v80, v74, v75
	v_cvt_pk_bf16_f32 v81, v76, v77
	v_cvt_pk_bf16_f32 v70, v70, v71
	v_cvt_pk_bf16_f32 v71, v72, v73
	v_cvt_pk_bf16_f32 v72, v66, v67
	v_cvt_pk_bf16_f32 v73, v68, v69
	v_mov_b32_e32 v74, v78
	v_mov_b32_e32 v75, v79
	v_mov_b32_e32 v76, v80
	v_mov_b32_e32 v77, v81
	v_mov_b32_dpp v78, v70 row_ror:8 row_mask:0xf bank_mask:0xc
	v_mov_b32_dpp v79, v71 row_ror:8 row_mask:0xf bank_mask:0xc
	v_mov_b32_dpp v80, v72 row_ror:8 row_mask:0xf bank_mask:0xc
	v_mov_b32_dpp v81, v73 row_ror:8 row_mask:0xf bank_mask:0xc
	v_mov_b32_dpp v70, v74 row_ror:8 row_mask:0xf bank_mask:0x3
	v_mov_b32_dpp v71, v75 row_ror:8 row_mask:0xf bank_mask:0x3
	v_mov_b32_dpp v72, v76 row_ror:8 row_mask:0xf bank_mask:0x3
	v_mov_b32_dpp v73, v77 row_ror:8 row_mask:0xf bank_mask:0x3
	s_add_u32 s98, s98, 0x10000
	s_addc_u32 s99, s99, 0
	global_store_dwordx4 v148, v[78:81], s[98:99] nt
	s_add_u32 s98, s98, 0x10000
	s_addc_u32 s99, s99, 0
	global_store_dwordx4 v148, v[70:73], s[98:99] nt
	v_max_f32_e32 v58, 0, v58
	v_max_f32_e32 v59, 0, v59
	v_max_f32_e32 v60, 0, v60
	v_max_f32_e32 v61, 0, v61
	v_max_f32_e32 v62, 0, v62
	v_max_f32_e32 v63, 0, v63
	v_max_f32_e32 v64, 0, v64
	v_max_f32_e32 v65, 0, v65
	v_max_f32_e32 v50, 0, v50
	v_max_f32_e32 v51, 0, v51
	v_max_f32_e32 v52, 0, v52
	v_max_f32_e32 v53, 0, v53
	v_max_f32_e32 v54, 0, v54
	v_max_f32_e32 v55, 0, v55
	v_max_f32_e32 v56, 0, v56
	v_max_f32_e32 v57, 0, v57
	v_mul_f32_e32 v58, v58, v58
	v_mul_f32_e32 v59, v59, v59
	v_mul_f32_e32 v60, v60, v60
	v_mul_f32_e32 v61, v61, v61
	v_mul_f32_e32 v62, v62, v62
	v_mul_f32_e32 v63, v63, v63
	v_mul_f32_e32 v64, v64, v64
	v_mul_f32_e32 v65, v65, v65
	v_mul_f32_e32 v50, v50, v50
	v_mul_f32_e32 v51, v51, v51
	v_mul_f32_e32 v52, v52, v52
	v_mul_f32_e32 v53, v53, v53
	v_mul_f32_e32 v54, v54, v54
	v_mul_f32_e32 v55, v55, v55
	v_mul_f32_e32 v56, v56, v56
	v_mul_f32_e32 v57, v57, v57
	v_cvt_pk_bf16_f32 v62, v62, v63
	v_cvt_pk_bf16_f32 v63, v64, v65
	v_cvt_pk_bf16_f32 v64, v58, v59
	v_cvt_pk_bf16_f32 v65, v60, v61
	v_cvt_pk_bf16_f32 v54, v54, v55
	v_cvt_pk_bf16_f32 v55, v56, v57
	v_cvt_pk_bf16_f32 v56, v50, v51
	v_cvt_pk_bf16_f32 v57, v52, v53
	v_mov_b32_e32 v58, v62
	v_mov_b32_e32 v59, v63
	v_mov_b32_e32 v60, v64
	v_mov_b32_e32 v61, v65
	v_mov_b32_dpp v62, v54 row_ror:8 row_mask:0xf bank_mask:0xc
	v_mov_b32_dpp v63, v55 row_ror:8 row_mask:0xf bank_mask:0xc
	v_mov_b32_dpp v64, v56 row_ror:8 row_mask:0xf bank_mask:0xc
	v_mov_b32_dpp v65, v57 row_ror:8 row_mask:0xf bank_mask:0xc
	v_mov_b32_dpp v54, v58 row_ror:8 row_mask:0xf bank_mask:0x3
	v_mov_b32_dpp v55, v59 row_ror:8 row_mask:0xf bank_mask:0x3
	v_mov_b32_dpp v56, v60 row_ror:8 row_mask:0xf bank_mask:0x3
	v_mov_b32_dpp v57, v61 row_ror:8 row_mask:0xf bank_mask:0x3
	s_add_u32 s98, s98, 0x90000
	s_addc_u32 s99, s99, 0
	global_store_dwordx4 v148, v[62:65], s[98:99] nt
	s_add_u32 s98, s98, 0x10000
	s_addc_u32 s99, s99, 0
	global_store_dwordx4 v148, v[54:57], s[98:99] nt
	v_max_f32_e32 v42, 0, v42
	v_max_f32_e32 v43, 0, v43
	v_max_f32_e32 v44, 0, v44
	v_max_f32_e32 v45, 0, v45
	v_max_f32_e32 v46, 0, v46
	v_max_f32_e32 v47, 0, v47
	v_max_f32_e32 v48, 0, v48
	v_max_f32_e32 v49, 0, v49
	v_max_f32_e32 v34, 0, v34
	v_max_f32_e32 v35, 0, v35
	v_max_f32_e32 v36, 0, v36
	v_max_f32_e32 v37, 0, v37
	v_max_f32_e32 v38, 0, v38
	v_max_f32_e32 v39, 0, v39
	v_max_f32_e32 v40, 0, v40
	v_max_f32_e32 v41, 0, v41
	v_mul_f32_e32 v42, v42, v42
	v_mul_f32_e32 v43, v43, v43
	v_mul_f32_e32 v44, v44, v44
	v_mul_f32_e32 v45, v45, v45
	v_mul_f32_e32 v46, v46, v46
	v_mul_f32_e32 v47, v47, v47
	v_mul_f32_e32 v48, v48, v48
	v_mul_f32_e32 v49, v49, v49
	v_mul_f32_e32 v34, v34, v34
	v_mul_f32_e32 v35, v35, v35
	v_mul_f32_e32 v36, v36, v36
	v_mul_f32_e32 v37, v37, v37
	v_mul_f32_e32 v38, v38, v38
	v_mul_f32_e32 v39, v39, v39
	v_mul_f32_e32 v40, v40, v40
	v_mul_f32_e32 v41, v41, v41
	v_cvt_pk_bf16_f32 v46, v46, v47
	v_cvt_pk_bf16_f32 v47, v48, v49
	v_cvt_pk_bf16_f32 v48, v42, v43
	v_cvt_pk_bf16_f32 v49, v44, v45
	v_cvt_pk_bf16_f32 v38, v38, v39
	v_cvt_pk_bf16_f32 v39, v40, v41
	v_cvt_pk_bf16_f32 v40, v34, v35
	v_cvt_pk_bf16_f32 v41, v36, v37
	v_mov_b32_e32 v42, v46
	v_mov_b32_e32 v43, v47
	v_mov_b32_e32 v44, v48
	v_mov_b32_e32 v45, v49
	v_mov_b32_dpp v46, v38 row_ror:8 row_mask:0xf bank_mask:0xc
	v_mov_b32_dpp v47, v39 row_ror:8 row_mask:0xf bank_mask:0xc
	v_mov_b32_dpp v48, v40 row_ror:8 row_mask:0xf bank_mask:0xc
	v_mov_b32_dpp v49, v41 row_ror:8 row_mask:0xf bank_mask:0xc
	v_mov_b32_dpp v38, v42 row_ror:8 row_mask:0xf bank_mask:0x3
	v_mov_b32_dpp v39, v43 row_ror:8 row_mask:0xf bank_mask:0x3
	v_mov_b32_dpp v40, v44 row_ror:8 row_mask:0xf bank_mask:0x3
	v_mov_b32_dpp v41, v45 row_ror:8 row_mask:0xf bank_mask:0x3
	s_add_u32 s98, s98, 0x10000
	s_addc_u32 s99, s99, 0
	global_store_dwordx4 v148, v[46:49], s[98:99] nt
	s_add_u32 s98, s98, 0x10000
	s_addc_u32 s99, s99, 0
	global_store_dwordx4 v148, v[38:41], s[98:99] nt
	v_max_f32_e32 v26, 0, v26
	v_max_f32_e32 v27, 0, v27
	v_max_f32_e32 v28, 0, v28
	v_max_f32_e32 v29, 0, v29
	v_max_f32_e32 v30, 0, v30
	v_max_f32_e32 v31, 0, v31
	v_max_f32_e32 v32, 0, v32
	v_max_f32_e32 v33, 0, v33
	v_max_f32_e32 v18, 0, v18
	v_max_f32_e32 v19, 0, v19
	v_max_f32_e32 v20, 0, v20
	v_max_f32_e32 v21, 0, v21
	v_max_f32_e32 v22, 0, v22
	v_max_f32_e32 v23, 0, v23
	v_max_f32_e32 v24, 0, v24
	v_max_f32_e32 v25, 0, v25
	v_mul_f32_e32 v26, v26, v26
	v_mul_f32_e32 v27, v27, v27
	v_mul_f32_e32 v28, v28, v28
	v_mul_f32_e32 v29, v29, v29
	v_mul_f32_e32 v30, v30, v30
	v_mul_f32_e32 v31, v31, v31
	v_mul_f32_e32 v32, v32, v32
	v_mul_f32_e32 v33, v33, v33
	v_mul_f32_e32 v18, v18, v18
	v_mul_f32_e32 v19, v19, v19
	v_mul_f32_e32 v20, v20, v20
	v_mul_f32_e32 v21, v21, v21
	v_mul_f32_e32 v22, v22, v22
	v_mul_f32_e32 v23, v23, v23
	v_mul_f32_e32 v24, v24, v24
	v_mul_f32_e32 v25, v25, v25
	v_cvt_pk_bf16_f32 v30, v30, v31
	v_cvt_pk_bf16_f32 v31, v32, v33
	v_cvt_pk_bf16_f32 v32, v26, v27
	v_cvt_pk_bf16_f32 v33, v28, v29
	v_cvt_pk_bf16_f32 v22, v22, v23
	v_cvt_pk_bf16_f32 v23, v24, v25
	v_cvt_pk_bf16_f32 v24, v18, v19
	v_cvt_pk_bf16_f32 v25, v20, v21
	v_mov_b32_e32 v26, v30
	v_mov_b32_e32 v27, v31
	v_mov_b32_e32 v28, v32
	v_mov_b32_e32 v29, v33
	v_mov_b32_dpp v30, v22 row_ror:8 row_mask:0xf bank_mask:0xc
	v_mov_b32_dpp v31, v23 row_ror:8 row_mask:0xf bank_mask:0xc
	v_mov_b32_dpp v32, v24 row_ror:8 row_mask:0xf bank_mask:0xc
	v_mov_b32_dpp v33, v25 row_ror:8 row_mask:0xf bank_mask:0xc
	v_mov_b32_dpp v22, v26 row_ror:8 row_mask:0xf bank_mask:0x3
	v_mov_b32_dpp v23, v27 row_ror:8 row_mask:0xf bank_mask:0x3
	v_mov_b32_dpp v24, v28 row_ror:8 row_mask:0xf bank_mask:0x3
	v_mov_b32_dpp v25, v29 row_ror:8 row_mask:0xf bank_mask:0x3
	s_add_u32 s98, s98, 0x10000
	s_addc_u32 s99, s99, 0
	global_store_dwordx4 v148, v[30:33], s[98:99] nt
	s_add_u32 s98, s98, 0x10000
	s_addc_u32 s99, s99, 0
	global_store_dwordx4 v148, v[22:25], s[98:99] nt
	v_max_f32_e32 v10, 0, v10
	v_max_f32_e32 v11, 0, v11
	v_max_f32_e32 v12, 0, v12
	v_max_f32_e32 v13, 0, v13
	v_max_f32_e32 v14, 0, v14
	v_max_f32_e32 v15, 0, v15
	v_max_f32_e32 v16, 0, v16
	v_max_f32_e32 v17, 0, v17
	v_max_f32_e32 v2, 0, v2
	v_max_f32_e32 v3, 0, v3
	v_max_f32_e32 v4, 0, v4
	v_max_f32_e32 v5, 0, v5
	v_max_f32_e32 v6, 0, v6
	v_max_f32_e32 v7, 0, v7
	v_max_f32_e32 v8, 0, v8
	v_max_f32_e32 v9, 0, v9
	v_mul_f32_e32 v10, v10, v10
	v_mul_f32_e32 v11, v11, v11
	v_mul_f32_e32 v12, v12, v12
	v_mul_f32_e32 v13, v13, v13
	v_mul_f32_e32 v14, v14, v14
	v_mul_f32_e32 v15, v15, v15
	v_mul_f32_e32 v16, v16, v16
	v_mul_f32_e32 v17, v17, v17
	v_mul_f32_e32 v2, v2, v2
	v_mul_f32_e32 v3, v3, v3
	v_mul_f32_e32 v4, v4, v4
	v_mul_f32_e32 v5, v5, v5
	v_mul_f32_e32 v6, v6, v6
	v_mul_f32_e32 v7, v7, v7
	v_mul_f32_e32 v8, v8, v8
	v_mul_f32_e32 v9, v9, v9
	v_cvt_pk_bf16_f32 v14, v14, v15
	v_cvt_pk_bf16_f32 v15, v16, v17
	v_cvt_pk_bf16_f32 v16, v10, v11
	v_cvt_pk_bf16_f32 v17, v12, v13
	v_cvt_pk_bf16_f32 v6, v6, v7
	v_cvt_pk_bf16_f32 v7, v8, v9
	v_cvt_pk_bf16_f32 v8, v2, v3
	v_cvt_pk_bf16_f32 v9, v4, v5
	v_mov_b32_e32 v10, v14
	v_mov_b32_e32 v11, v15
	v_mov_b32_e32 v12, v16
	v_mov_b32_e32 v13, v17
	v_mov_b32_dpp v14, v6 row_ror:8 row_mask:0xf bank_mask:0xc
	v_mov_b32_dpp v15, v7 row_ror:8 row_mask:0xf bank_mask:0xc
	v_mov_b32_dpp v16, v8 row_ror:8 row_mask:0xf bank_mask:0xc
	v_mov_b32_dpp v17, v9 row_ror:8 row_mask:0xf bank_mask:0xc
	v_mov_b32_dpp v6, v10 row_ror:8 row_mask:0xf bank_mask:0x3
	v_mov_b32_dpp v7, v11 row_ror:8 row_mask:0xf bank_mask:0x3
	v_mov_b32_dpp v8, v12 row_ror:8 row_mask:0xf bank_mask:0x3
	v_mov_b32_dpp v9, v13 row_ror:8 row_mask:0xf bank_mask:0x3
	s_add_u32 s98, s98, 0x10000
	s_addc_u32 s99, s99, 0
	global_store_dwordx4 v148, v[14:17], s[98:99] nt
	s_add_u32 s98, s98, 0x10000
	s_addc_u32 s99, s99, 0
	global_store_dwordx4 v148, v[6:9], s[98:99] nt
	s_andn2_b64 vcc, exec, s[0:1]
	s_mov_b64 s[0:1], -1
	s_mov_b32 s98, 1
	s_cbranch_vccnz .LBB0_772
	s_andn2_b64 vcc, exec, s[10:11]
	s_cbranch_vccnz .LBB0_771
	s_barrier
	s_branch .LBB0_771

	.amdhsa_kernel _Z13moba_gmlp_fwd4Args
		.amdhsa_group_segment_fixed_size 0
		.amdhsa_private_segment_fixed_size 0
		.amdhsa_kernarg_size 400
		.amdhsa_user_sgpr_count 2
		.amdhsa_user_sgpr_dispatch_ptr 0
		.amdhsa_user_sgpr_queue_ptr 0
		.amdhsa_user_sgpr_kernarg_segment_ptr 1
		.amdhsa_user_sgpr_dispatch_id 0
		.amdhsa_user_sgpr_kernarg_preload_length 0
		.amdhsa_user_sgpr_kernarg_preload_offset 0
		.amdhsa_user_sgpr_private_segment_size 0
		.amdhsa_uses_dynamic_stack 0
		.amdhsa_enable_private_segment 0
		.amdhsa_system_sgpr_workgroup_id_x 1
		.amdhsa_system_sgpr_workgroup_id_y 0
		.amdhsa_system_sgpr_workgroup_id_z 0
		.amdhsa_system_sgpr_workgroup_info 0
		.amdhsa_system_vgpr_workitem_id 0
		.amdhsa_next_free_vgpr 250
		.amdhsa_next_free_sgpr 102
		.amdhsa_accum_offset 252
		.amdhsa_reserve_vcc 1
		.amdhsa_float_round_mode_32 0
		.amdhsa_float_round_mode_16_64 0
		.amdhsa_float_denorm_mode_32 3
		.amdhsa_float_denorm_mode_16_64 3
		.amdhsa_dx10_clamp 1
		.amdhsa_ieee_mode 1
		.amdhsa_fp16_overflow 0
		.amdhsa_tg_split 0
		.amdhsa_exception_fp_ieee_invalid_op 0
		.amdhsa_exception_fp_denorm_src 0
		.amdhsa_exception_fp_ieee_div_zero 0
		.amdhsa_exception_fp_ieee_overflow 0
		.amdhsa_exception_fp_ieee_underflow 0
		.amdhsa_exception_fp_ieee_inexact 0
		.amdhsa_exception_int_div_zero 0
	.end_amdhsa_kernel

amdhsa.kernels:
  - .agpr_count:     0
    .args:
      - .offset:         0
        .size:           144
        .value_kind:     by_value
      - .offset:         144
        .size:           4
        .value_kind:     hidden_block_count_x
      - .offset:         148
        .size:           4
        .value_kind:     hidden_block_count_y
      - .offset:         152
        .size:           4
        .value_kind:     hidden_block_count_z
      - .offset:         156
        .size:           2
        .value_kind:     hidden_group_size_x
      - .offset:         158
        .size:           2
        .value_kind:     hidden_group_size_y
      - .offset:         160
        .size:           2
        .value_kind:     hidden_group_size_z
      - .offset:         162
        .size:           2
        .value_kind:     hidden_remainder_x
      - .offset:         164
        .size:           2
        .value_kind:     hidden_remainder_y
      - .offset:         166
        .size:           2
        .value_kind:     hidden_remainder_z
      - .offset:         184
        .size:           8
        .value_kind:     hidden_global_offset_x
      - .offset:         192
        .size:           8
        .value_kind:     hidden_global_offset_y
      - .offset:         200
        .size:           8
        .value_kind:     hidden_global_offset_z
      - .offset:         208
        .size:           2
        .value_kind:     hidden_grid_dims
      - .offset:         264
        .size:           4
        .value_kind:     hidden_dynamic_lds_size
    .group_segment_fixed_size: 0
    .kernarg_segment_align: 8
    .kernarg_segment_size: 400
    .language:       OpenCL C
    .language_version:
      - 2
      - 0
    .max_flat_workgroup_size: 512
    .name:           _Z13moba_gmlp_fwd4Args
    .private_segment_fixed_size: 0
    .sgpr_count:     108
    .sgpr_spill_count: 4
    .symbol:         _Z13moba_gmlp_fwd4Args.kd
    .uniform_work_group_size: 1
    .uses_dynamic_stack: false
    .vgpr_count:     250
    .vgpr_spill_count: 0
    .wavefront_size: 64
